# attention loop: K tile LDS-DMA issued in the MFMA-bound tail of the step one tile further ahead (waves 0-3 and 4-7 at different points), closing wait leaves it in flight (vmcnt(1))
# baseline (speedup 1.0000x reference)
; #define SB() __builtin_amdgcn_sched_barrier(0)
; #define MF32(a,b,c) __builtin_amdgcn_mfma_f32_32x32x16_bf16(a,b,c,0,0,0)
; #define EXP1(x) x=__builtin_amdgcn_exp2f((x)-mh_)
; __device__ __forceinline__ bf16x8 vfrag(lds_cptr vp,int i){ const s16x4 lo=vtr(vp+(i&3)*4096+(i>>2)*1024), hh=vtr(vp+(i&3)*4096+(i>>2)*1024+512); return (bf16x8){lo[0],lo[1],lo[2],lo[3],hh[0],hh[1],hh[2],hh[3]}; }
; __device__ __forceinline__ u32x4 packw(const f32x16&p,int base){ u32x4 w; w[0]=cvtpk_s(p[base],p[base+1]); w[1]=cvtpk_s(p[base+2],p[base+3]); w[2]=cvtpk_s(p[base+4],p[base+5]); w[3]=cvtpk_s(p[base+6],p[base+7]); return w; }
; template<int THRL,bool FIRST> __device__ __forceinline__ void step_main(f32x16&p0,f32x16&p1,f32x16&n0,f32x16&n1,St&S,lds_cptr kpn,lds_cptr qp,lds_cptr vp,float*wsf,int r32,int hi,float&rm){
;     ...
;   bf16x8 ka=KF(0),kb=KF(1),kc=KF(2),kd=KF(3),qa=QF(0),qb=QF(1);
;   decide<THRL,FIRST>(rm,S,wsf,r32,hi);
;   u32x4 pw0,pw1,pw2,pw3; const float mh_=S.mhat; const f32x16 z=f32x16{};
;   SB();
;   n0=MF32(ka,qa,z); ka=KF(4); EXP1(p0[0]);EXP1(p0[1]);EXP1(p0[2]); SB();
;   n1=MF32(kb,qa,z); kb=KF(5); qa=QF(2); EXP1(p0[3]);EXP1(p0[4]);EXP1(p0[5]); SB();
;   n0=MF32(kc,qb,n0);   kc=KF(6); EXP1(p0[6]);EXP1(p0[7]);EXP1(p0[8]); SB();
;   n1=MF32(kd,qb,n1);   kd=KF(7); qb=QF(3); EXP1(p0[9]);EXP1(p0[10]);EXP1(p0[11]); SB();
;   bf16x8 vfa=vfrag(vp,0);
;   n0=MF32(ka,qa,n0);   EXP1(p0[12]);EXP1(p0[13]);EXP1(p0[14]); pw0=packw(p0,0); SB();
;   bf16x8 vfb=vfrag(vp,1);
;   n1=MF32(kb,qa,n1);   EXP1(p0[15]);EXP1(p1[0]);EXP1(p1[1]); SB();
;   bf16x8 vfc=vfrag(vp,2);
;   n0=MF32(kc,qb,n0);   EXP1(p1[2]);EXP1(p1[3]);EXP1(p1[4]); pw1=packw(p0,8); SB();
;   bf16x8 vfd=vfrag(vp,3);
;   n1=MF32(kd,qb,n1);   EXP1(p1[5]);EXP1(p1[6]);EXP1(p1[7]); SB();
;     ...
;   float sa=p0[0]+p0[1];
;     ...
;   PVG(0,pw0,vfa,4, p0[2],p0[3],p0[4],p0[5],   do{EXP1(p1[8]);EXP1(p1[9]);}while(0));
;   PVG(1,pw0,vfb,5, p0[6],p0[7],p0[8],p0[9], do{EXP1(p1[10]);EXP1(p1[11]);}while(0));
;   PVG(2,pw0,vfc,6, p0[10],p0[11],p0[12],p0[13], do{EXP1(p1[12]);EXP1(p1[13]);}while(0));
;   PVG(3,pw0,vfd,7, p0[14],p0[15],p1[0],p1[1],   do{EXP1(p1[14]);EXP1(p1[15]);}while(0));
;   PVG(4,pw1,vfa,8, p1[2],p1[3],p1[4],p1[5],   pw2=packw(p1,0));
;   PVG(5,pw1,vfb,9, p1[6],p1[7],p1[8],p1[9], pw3=packw(p1,8));
;   PVG(6,pw1,vfc,10, p1[10],p1[11],p1[12],p1[13], do{}while(0));
;   PVG(7,pw1,vfd,11, p1[14],p1[15],0.f,0.f, do{}while(0));
.LBB0_275:
	s_waitcnt lgkmcnt(1)
	v_mfma_f32_32x32x16_bf16 v[98:113], v[218:221], v[214:217], 0
	ds_read_b128 v[178:181], v249 offset:20480
	v_sub_f32_e32 v82, v131, v247
	v_sub_f32_e32 v17, v130, v247
	v_exp_f32_e32 v190, v82
	v_sub_f32_e32 v82, v132, v247
	v_exp_f32_e32 v17, v17
	v_exp_f32_e32 v191, v82
	v_sub_f32_e32 v82, v133, v247
	v_exp_f32_e32 v192, v82
	v_sub_f32_e32 v82, v134, v247
	v_exp_f32_e32 v193, v82
	v_sub_f32_e32 v82, v135, v247
	v_exp_f32_e32 v194, v82
	v_mfma_f32_32x32x16_bf16 v[82:97], v[210:213], v[214:217], 0
	ds_read_b128 v[182:185], v249 offset:20992
	ds_read_b128 v[186:189], v248 offset:2048
	s_waitcnt lgkmcnt(3)
	v_mfma_f32_32x32x16_bf16 v[98:113], v[12:15], v[8:11], v[98:113]
	ds_read_b128 v[130:133], v249 offset:22528
	v_sub_f32_e32 v134, v136, v247
	v_exp_f32_e32 v195, v134
	v_sub_f32_e32 v134, v137, v247
	v_exp_f32_e32 v196, v134
	v_sub_f32_e32 v134, v138, v247
	v_exp_f32_e32 v197, v134
	v_mfma_f32_32x32x16_bf16 v[82:97], v[4:7], v[8:11], v[82:97]
	ds_read_b128 v[12:15], v249 offset:23040
	ds_read_b128 v[134:137], v248 offset:3072
	v_sub_f32_e32 v138, v139, v247
	v_exp_f32_e32 v198, v138
	v_sub_f32_e32 v138, v140, v247
	v_exp_f32_e32 v199, v138
	v_sub_f32_e32 v138, v141, v247
	v_exp_f32_e32 v200, v138
	s_waitcnt lgkmcnt(3)
	v_mfma_f32_32x32x16_bf16 v[98:113], v[178:181], v[186:189], v[98:113]
	ds_read_b64_tr_b16 v[4:5], v246 offset:40960
	ds_read_b64_tr_b16 v[6:7], v246 offset:41472
	v_sub_f32_e32 v8, v142, v247
	v_exp_f32_e32 v201, v8
	v_sub_f32_e32 v8, v143, v247
	v_exp_f32_e32 v202, v8
	v_sub_f32_e32 v8, v144, v247
	v_exp_f32_e32 v179, v8
	v_cvt_pk_bf16_f32 v8, v17, v190
	v_cvt_pk_bf16_f32 v9, v191, v192
	v_cvt_pk_bf16_f32 v10, v193, v194
	v_cvt_pk_bf16_f32 v11, v195, v196
	v_mfma_f32_32x32x16_bf16 v[82:97], v[182:185], v[186:189], v[82:97]
	ds_read_b64_tr_b16 v[138:139], v246 offset:45056
	ds_read_b64_tr_b16 v[140:141], v246 offset:45568
	v_sub_f32_e32 v114, v114, v247
	v_sub_f32_e32 v142, v145, v247
	v_exp_f32_e32 v181, v114
	v_sub_f32_e32 v114, v115, v247
	v_exp_f32_e32 v180, v142
	v_exp_f32_e32 v203, v114
	s_waitcnt lgkmcnt(4)
	v_mfma_f32_32x32x16_bf16 v[98:113], v[130:133], v[134:137], v[98:113]
	ds_read_b64_tr_b16 v[142:143], v246 offset:49152
	ds_read_b64_tr_b16 v[144:145], v246 offset:49664
	v_sub_f32_e32 v114, v116, v247
	v_exp_f32_e32 v182, v114
	v_sub_f32_e32 v114, v117, v247
	v_exp_f32_e32 v183, v114
	v_sub_f32_e32 v114, v118, v247
	v_exp_f32_e32 v184, v114
	v_cvt_pk_bf16_f32 v114, v197, v198
	v_cvt_pk_bf16_f32 v115, v199, v200
	v_cvt_pk_bf16_f32 v116, v201, v202
	v_cvt_pk_bf16_f32 v117, v179, v180
	v_mfma_f32_32x32x16_bf16 v[82:97], v[12:15], v[134:137], v[82:97]
	ds_read_b64_tr_b16 v[130:131], v246 offset:53248
	ds_read_b64_tr_b16 v[132:133], v246 offset:53760
	v_sub_f32_e32 v118, v119, v247
	v_exp_f32_e32 v185, v118
	v_sub_f32_e32 v118, v120, v247
	v_exp_f32_e32 v186, v118
	v_sub_f32_e32 v118, v121, v247
	v_exp_f32_e32 v187, v118
	s_waitcnt lgkmcnt(6)
	v_mfma_f32_32x32x16_bf16 v[18:33], v[8:11], v[4:7], v[18:33]
	ds_read_b64_tr_b16 v[12:13], v246 offset:41984
	ds_read_b64_tr_b16 v[14:15], v246 offset:42496
	v_sub_f32_e32 v118, v122, v247
	v_exp_f32_e32 v134, v118
	v_sub_f32_e32 v118, v123, v247
	v_exp_f32_e32 v135, v118
	s_waitcnt lgkmcnt(6)
	v_mfma_f32_32x32x16_bf16 v[34:49], v[8:11], v[138:141], v[34:49]
	ds_read_b64_tr_b16 v[4:5], v246 offset:46080
	ds_read_b64_tr_b16 v[6:7], v246 offset:46592
	v_sub_f32_e32 v118, v124, v247
	v_exp_f32_e32 v136, v118
	v_sub_f32_e32 v118, v125, v247
	v_exp_f32_e32 v137, v118
	s_waitcnt lgkmcnt(6)
	v_mfma_f32_32x32x16_bf16 v[50:65], v[8:11], v[142:145], v[50:65]
	ds_read_b64_tr_b16 v[118:119], v246 offset:50176
	ds_read_b64_tr_b16 v[120:121], v246 offset:50688
	v_sub_f32_e32 v122, v126, v247
	v_exp_f32_e32 v138, v122
	v_sub_f32_e32 v122, v127, v247
	v_exp_f32_e32 v139, v122
	s_waitcnt lgkmcnt(6)
	v_mfma_f32_32x32x16_bf16 v[66:81], v[8:11], v[130:133], v[66:81]
	ds_read_b64_tr_b16 v[122:123], v246 offset:54272
	ds_read_b64_tr_b16 v[124:125], v246 offset:54784
	v_sub_f32_e32 v126, v128, v247
	v_exp_f32_e32 v140, v126
	v_sub_f32_e32 v126, v129, v247
	v_exp_f32_e32 v141, v126
	s_waitcnt lgkmcnt(6)
	v_mfma_f32_32x32x16_bf16 v[18:33], v[114:117], v[12:15], v[18:33]
	ds_read_b64_tr_b16 v[8:9], v246 offset:43008
	ds_read_b64_tr_b16 v[10:11], v246 offset:43520
	v_cvt_pk_bf16_f32 v126, v181, v203
	v_cvt_pk_bf16_f32 v127, v182, v183
	v_cvt_pk_bf16_f32 v128, v184, v185
	v_cvt_pk_bf16_f32 v129, v186, v187
	s_waitcnt lgkmcnt(6)
	v_mfma_f32_32x32x16_bf16 v[34:49], v[114:117], v[4:7], v[34:49]
	ds_read_b64_tr_b16 v[12:13], v246 offset:47104
	ds_read_b64_tr_b16 v[14:15], v246 offset:47616
	v_cvt_pk_bf16_f32 v130, v134, v135
	v_cvt_pk_bf16_f32 v131, v136, v137
	v_cvt_pk_bf16_f32 v132, v138, v139
	v_cvt_pk_bf16_f32 v133, v140, v141
	s_waitcnt lgkmcnt(6)
	v_mfma_f32_32x32x16_bf16 v[50:65], v[114:117], v[118:121], v[50:65]
	ds_read_b64_tr_b16 v[4:5], v246 offset:51200
	ds_read_b64_tr_b16 v[6:7], v246 offset:51712
	s_waitcnt lgkmcnt(6)
	v_mfma_f32_32x32x16_bf16 v[66:81], v[114:117], v[122:125], v[66:81]
	ds_read_b64_tr_b16 v[118:119], v246 offset:55296
	ds_read_b64_tr_b16 v[120:121], v246 offset:55808
	s_waitcnt lgkmcnt(6)
; __device__ __forceinline__ float max3f(float a,float b,float c){float r;asm("v_max3_f32 %0, %1, %2, %3":"=v"(r):"v"(a),"v"(b),"v"(c));return r;}
; __device__ __forceinline__ float max2f(float a,float b){float r;asm("v_max_f32_e32 %0, %1, %2":"=v"(r):"v"(a),"v"(b));return r;}
; #define A128_WAITBAR() asm volatile("s_waitcnt vmcnt(0) lgkmcnt(0)\n\ts_barrier":::"memory")
;   #define PINAB() asm volatile("":"+v"(ma),"+v"(mb))
;   #define ROT() do{ ks1=ks2; ks2=(ks2==2*KBUF)?0:ks2+KBUF; }while(0)
; template<int THRL,bool FIRST> __device__ __forceinline__ void step_main(f32x16&p0,f32x16&p1,f32x16&n0,f32x16&n1,St&S,lds_cptr kpn,lds_cptr qp,lds_cptr vp,float*wsf,int r32,int hi,float&rm){
;     ...
;   float ma,mb;
;     ...
;   PVG(8,pw2,vfa,12,0.f,0.f,0.f,0.f, do{ma=max3f(n0[0],n0[1],n1[0]);mb=max3f(n0[2],n0[3],n1[1]);PINAB();}while(0));
;   PVG(9,pw2,vfb,13,0.f,0.f,0.f,0.f, do{ma=max3f(ma,n1[2],n1[3]);mb=max3f(mb,n0[4],n0[5]);PINAB();}while(0));
;   PVG(10,pw2,vfc,14,0.f,0.f,0.f,0.f, do{ma=max3f(ma,n0[6],n0[7]);mb=max3f(mb,n1[4],n1[5]);PINAB();}while(0));
;   PVG(11,pw2,vfd,15,0.f,0.f,0.f,0.f, do{ma=max3f(ma,n1[6],n1[7]);mb=max3f(mb,n0[8],n0[9]);PINAB();}while(0));
;   PVG(12,pw3,vfa,16,0.f,0.f,0.f,0.f, do{ma=max3f(ma,n0[10],n0[11]);mb=max3f(mb,n1[8],n1[9]);PINAB();}while(0));
;   PVG(13,pw3,vfb,16,0.f,0.f,0.f,0.f, do{ma=max3f(ma,n1[10],n1[11]);mb=max3f(mb,n0[12],n0[13]);PINAB();}while(0));
;   PVG(14,pw3,vfc,16,0.f,0.f,0.f,0.f, do{ma=max3f(ma,n0[14],n0[15]);mb=max3f(mb,n1[12],n1[13]);PINAB();}while(0));
;   PVG(15,pw3,vfd,16,0.f,0.f,0.f,0.f, do{ma=max3f(ma,n1[14],n1[15]);ma=max2f(ma,mb);PINAB();}while(0));
;     ...
;   { auto rr=__builtin_amdgcn_permlane32_swap(__float_as_uint(ma),__float_as_uint(ma),false,false); rm=max2f(__uint_as_float(rr[0]),__uint_as_float(rr[1])); }
;     ...
;   S.l_reg+=sa;
; template<int THRL> __device__ __forceinline__ void unit(int qb,const bf16*Q,const bf16*K,const bf16*V,bf16*O,char*shm){
;     ...
;     DMA_K(2,ks2); DMA_V(1,VBUF);
;     step_main<THRL,true>(pA0,pA1,pB0,pB1,S,kp0+ks1,qp,vp0,wsf,r32,hi,rm); A128_WAITBAR(); ROT();
;     DMA_K(3,ks2); DMA_V(2,0);
;     step_main<THRL,false>(pB0,pB1,pA0,pA1,S,kp0+ks1,qp,vp0+VBUF,wsf,r32,hi,rm); A128_WAITBAR(); ROT();
;     for(t=2;t<NT-4;t+=2){
;       DMA_K(t+2,ks2); DMA_V(t+1,VBUF);
;       step_main<THRL,false>(pA0,pA1,pB0,pB1,S,kp0+ks1,qp,vp0,wsf,r32,hi,rm); A128_WAITBAR(); ROT();
	v_mfma_f32_32x32x16_bf16 v[18:33], v[126:129], v[8:11], v[18:33]
	ds_read_b64_tr_b16 v[114:115], v246 offset:44032
	ds_read_b64_tr_b16 v[116:117], v246 offset:44544
	v_max3_f32 v122, v98, v99, v82
	v_max3_f32 v123, v100, v101, v83
	s_nop 0
	s_waitcnt lgkmcnt(6)
	v_mfma_f32_32x32x16_bf16 v[34:49], v[126:129], v[12:15], v[34:49]
	ds_read_b64_tr_b16 v[8:9], v246 offset:48128
	ds_read_b64_tr_b16 v[10:11], v246 offset:48640
	v_max3_f32 v122, v122, v84, v85
	v_max3_f32 v123, v123, v102, v103
	s_nop 0
	s_waitcnt lgkmcnt(6)
	v_mfma_f32_32x32x16_bf16 v[50:65], v[126:129], v[4:7], v[50:65]
	ds_read_b64_tr_b16 v[12:13], v246 offset:52224
	ds_read_b64_tr_b16 v[14:15], v246 offset:52736
	v_max3_f32 v122, v122, v104, v105
	v_max3_f32 v123, v123, v86, v87
	s_nop 0
	s_waitcnt lgkmcnt(6)
	v_mfma_f32_32x32x16_bf16 v[66:81], v[126:129], v[118:121], v[66:81]
	ds_read_b64_tr_b16 v[4:5], v246 offset:56320
	ds_read_b64_tr_b16 v[6:7], v246 offset:56832
	v_max3_f32 v122, v122, v88, v89
	v_max3_f32 v123, v123, v106, v107
	s_nop 0
	s_waitcnt lgkmcnt(6)
	v_mfma_f32_32x32x16_bf16 v[18:33], v[130:133], v[114:117], v[18:33]
	v_max3_f32 v118, v122, v108, v109
	v_max3_f32 v119, v123, v90, v91
	s_nop 0
	s_waitcnt lgkmcnt(4)
	v_mfma_f32_32x32x16_bf16 v[34:49], v[130:133], v[8:11], v[34:49]
	v_max3_f32 v114, v118, v92, v93
	v_max3_f32 v115, v119, v110, v111
	s_nop 0
	s_waitcnt lgkmcnt(2)
	v_mfma_f32_32x32x16_bf16 v[50:65], v[130:133], v[12:15], v[50:65]
	v_max3_f32 v8, v114, v112, v113
	v_max3_f32 v9, v115, v94, v95
	s_nop 0
	s_waitcnt lgkmcnt(0)
	v_mfma_f32_32x32x16_bf16 v[66:81], v[130:133], v[4:7], v[66:81]
	v_max3_f32 v8, v8, v96, v97
	s_nop 0
	v_max_f32_e32 v8, v8, v9
	s_nop 0
	s_nop 0
	v_mov_b32_e32 v4, v8
	s_nop 1
	v_permlane32_swap_b32_e32 v8, v4
	v_max_f32_e32 v178, v8, v4
	v_add_f32_e32 v4, v17, v190
	v_add_f32_e32 v4, v191, v4
	v_add_f32_e32 v4, v192, v4
	v_add_f32_e32 v4, v193, v4
	v_add_f32_e32 v4, v194, v4
	v_add_f32_e32 v4, v195, v4
	v_add_f32_e32 v4, v196, v4
	v_add_f32_e32 v4, v197, v4
	v_add_f32_e32 v4, v198, v4
	v_add_f32_e32 v4, v199, v4
	v_add_f32_e32 v4, v200, v4
	v_add_f32_e32 v4, v201, v4
	v_add_f32_e32 v4, v202, v4
	v_add_f32_e32 v4, v179, v4
	v_add_f32_e32 v4, v180, v4
	v_add_f32_e32 v4, v181, v4
	v_add_f32_e32 v4, v203, v4
	v_add_f32_e32 v4, v182, v4
	v_add_f32_e32 v4, v183, v4
	v_add_f32_e32 v4, v184, v4
	v_add_f32_e32 v4, v185, v4
	v_add_f32_e32 v4, v186, v4
	v_add_f32_e32 v4, v187, v4
	v_add_f32_e32 v4, v134, v4
	v_add_f32_e32 v4, v135, v4
	v_add_f32_e32 v4, v136, v4
	v_add_f32_e32 v4, v137, v4
	v_add_f32_e32 v4, v138, v4
	v_add_f32_e32 v4, v139, v4
	v_add_f32_e32 v4, v140, v4
	s_waitcnt vmcnt(0) lgkmcnt(0)
	s_barrier
	v_add_f32_e32 v4, v141, v4
	v_add_f32_e32 v4, 0, v4
	s_add_i32 s89, s85, -4
	v_add_f32_e32 v251, v16, v4
	v_cmp_gt_u32_e64 s[6:7], 32, v243
	s_mov_b32 s90, 2
	v_lshl_add_u32 v16, v242, 2, s78
	s_movk_i32 s88, 0x2000
	s_mov_b32 s91, 0
	s_mov_b64 s[50:51], s[30:31]
	s_mov_b64 s[58:59], s[28:29]
	v_sub_f32_e32 v146, 0, v247
	v_sub_f32_e32 v147, 0, v247
	v_sub_f32_e32 v148, 0, v247
	v_sub_f32_e32 v149, 0, v247
	v_sub_f32_e32 v150, 0, v247
	v_sub_f32_e32 v151, 0, v247
	v_sub_f32_e32 v152, 0, v247
	v_sub_f32_e32 v153, 0, v247
	v_sub_f32_e32 v154, 0, v247
	v_sub_f32_e32 v155, 0, v247
	v_sub_f32_e32 v156, 0, v247
	v_sub_f32_e32 v157, 0, v247
	v_sub_f32_e32 v158, 0, v247
	v_sub_f32_e32 v159, 0, v247
	v_sub_f32_e32 v160, 0, v247
	v_sub_f32_e32 v161, 0, v247
	v_sub_f32_e32 v82, v82, v247
	v_sub_f32_e32 v83, v83, v247
	v_sub_f32_e32 v84, v84, v247
	v_sub_f32_e32 v85, v85, v247
	v_sub_f32_e32 v86, v86, v247
	v_sub_f32_e32 v87, v87, v247
	v_sub_f32_e32 v88, v88, v247
	v_sub_f32_e32 v89, v89, v247
	v_sub_f32_e32 v90, v90, v247
	v_sub_f32_e32 v91, v91, v247
	v_sub_f32_e32 v92, v92, v247
	v_sub_f32_e32 v93, v93, v247
	v_sub_f32_e32 v94, v94, v247
	v_sub_f32_e32 v95, v95, v247
	v_sub_f32_e32 v96, v96, v247
	v_sub_f32_e32 v97, v97, v247
	v_sub_f32_e32 v98, v98, v247
	v_sub_f32_e32 v99, v99, v247
	v_sub_f32_e32 v100, v100, v247
	v_sub_f32_e32 v101, v101, v247
	v_sub_f32_e32 v102, v102, v247
	v_sub_f32_e32 v103, v103, v247
	v_sub_f32_e32 v104, v104, v247
	v_sub_f32_e32 v105, v105, v247
	v_sub_f32_e32 v106, v106, v247
	v_sub_f32_e32 v107, v107, v247
	v_sub_f32_e32 v108, v108, v247
	v_sub_f32_e32 v109, v109, v247
	v_sub_f32_e32 v110, v110, v247
	v_sub_f32_e32 v111, v111, v247
	v_sub_f32_e32 v112, v112, v247
	v_sub_f32_e32 v113, v113, v247
	v_sub_f32_e32 v178, v178, v247
	s_add_u32 s60, s58, 0xfff40000
	s_addc_u32 s61, s59, -1
	s_add_i32 s4, s88, s84
	s_mov_b32 s5, m0
	s_mov_b32 m0, s4
	s_nop 0
	global_load_lds_dwordx4 v252, s[60:61]
	s_add_i32 s4, s84, 0x4000
	s_mov_b32 m0, s4
	s_nop 0
	global_load_lds_dwordx4 v252, s[58:59]
	s_mov_b32 m0, s5
	ds_read_b128 v[164:167], v248
	ds_read_b128 v[168:171], v248 offset:1024
	ds_read_b128 v[172:175], v248 offset:2048
	ds_read_b128 v[236:239], v248 offset:3072
	v_add_u32_e32 v240, s91, v249
	ds_read_b128 v[204:207], v240
	ds_read_b128 v[208:211], v240 offset:512
	ds_read_b128 v[212:215], v240 offset:2048
	ds_read_b128 v[216:219], v240 offset:2560
	ds_read_b128 v[220:223], v240 offset:4096
	ds_read_b128 v[224:227], v240 offset:4608
	ds_read_b128 v[228:231], v240 offset:6144
	ds_read_b128 v[232:235], v240 offset:6656
	s_waitcnt vmcnt(0) lgkmcnt(0)
	s_barrier
	s_branch .LBB0_278

; #define SB() __builtin_amdgcn_sched_barrier(0)
; #define MF32(a,b,c) __builtin_amdgcn_mfma_f32_32x32x16_bf16(a,b,c,0,0,0)
; #define EXP1(x) x=__builtin_amdgcn_exp2f((x)-mh_)
; __device__ __forceinline__ bf16x8 vfrag(lds_cptr vp,int i){ const s16x4 lo=vtr(vp+(i&3)*4096+(i>>2)*1024), hh=vtr(vp+(i&3)*4096+(i>>2)*1024+512); return (bf16x8){lo[0],lo[1],lo[2],lo[3],hh[0],hh[1],hh[2],hh[3]}; }
; __device__ __forceinline__ u32x4 packw(const f32x16&p,int base){ u32x4 w; w[0]=cvtpk_s(p[base],p[base+1]); w[1]=cvtpk_s(p[base+2],p[base+3]); w[2]=cvtpk_s(p[base+4],p[base+5]); w[3]=cvtpk_s(p[base+6],p[base+7]); return w; }
; template<int THRL,bool FIRST> __device__ __forceinline__ void step_main(f32x16&p0,f32x16&p1,f32x16&n0,f32x16&n1,St&S,lds_cptr kpn,lds_cptr qp,lds_cptr vp,float*wsf,int r32,int hi,float&rm){
;     ...
;   bf16x8 ka=KF(0),kb=KF(1),kc=KF(2),kd=KF(3),qa=QF(0),qb=QF(1);
;   decide<THRL,FIRST>(rm,S,wsf,r32,hi);
;   u32x4 pw0,pw1,pw2,pw3; const float mh_=S.mhat; const f32x16 z=f32x16{};
;   SB();
;   n0=MF32(ka,qa,z); ka=KF(4); EXP1(p0[0]);EXP1(p0[1]);EXP1(p0[2]); SB();
;   n1=MF32(kb,qa,z); kb=KF(5); qa=QF(2); EXP1(p0[3]);EXP1(p0[4]);EXP1(p0[5]); SB();
;   n0=MF32(kc,qb,n0);   kc=KF(6); EXP1(p0[6]);EXP1(p0[7]);EXP1(p0[8]); SB();
;   n1=MF32(kd,qb,n1);   kd=KF(7); qb=QF(3); EXP1(p0[9]);EXP1(p0[10]);EXP1(p0[11]); SB();
;   bf16x8 vfa=vfrag(vp,0);
;   n0=MF32(ka,qa,n0);   EXP1(p0[12]);EXP1(p0[13]);EXP1(p0[14]); pw0=packw(p0,0); SB();
;   bf16x8 vfb=vfrag(vp,1);
;   n1=MF32(kb,qa,n1);   EXP1(p0[15]);EXP1(p1[0]);EXP1(p1[1]); SB();
;   bf16x8 vfc=vfrag(vp,2);
;   n0=MF32(kc,qb,n0);   EXP1(p1[2]);EXP1(p1[3]);EXP1(p1[4]); pw1=packw(p0,8); SB();
;   bf16x8 vfd=vfrag(vp,3);
;   n1=MF32(kd,qb,n1);   EXP1(p1[5]);EXP1(p1[6]);EXP1(p1[7]); SB();
;     ...
;   float sa=p0[0]+p0[1];
;     ...
;   PVG(0,pw0,vfa,4, p0[2],p0[3],p0[4],p0[5],   do{EXP1(p1[8]);EXP1(p1[9]);}while(0));
;   PVG(1,pw0,vfb,5, p0[6],p0[7],p0[8],p0[9], do{EXP1(p1[10]);EXP1(p1[11]);}while(0));
;   PVG(2,pw0,vfc,6, p0[10],p0[11],p0[12],p0[13], do{EXP1(p1[12]);EXP1(p1[13]);}while(0));
;   PVG(3,pw0,vfd,7, p0[14],p0[15],p1[0],p1[1],   do{EXP1(p1[14]);EXP1(p1[15]);}while(0));
;   PVG(4,pw1,vfa,8, p1[2],p1[3],p1[4],p1[5],   pw2=packw(p1,0));
;   PVG(5,pw1,vfb,9, p1[6],p1[7],p1[8],p1[9], pw3=packw(p1,8));
;   PVG(6,pw1,vfc,10, p1[10],p1[11],p1[12],p1[13], do{}while(0));
;   PVG(7,pw1,vfd,11, p1[14],p1[15],0.f,0.f, do{}while(0));
.LBB0_277:
	s_add_i32 s90, s90, 2
	v_mfma_f32_32x32x16_bf16 v[98:113], v[204:207], v[164:167], v[146:161]
	v_exp_f32_e32 v130, v130
	v_exp_f32_e32 v131, v131
	v_exp_f32_e32 v132, v132
	v_exp_f32_e32 v133, v133
	v_exp_f32_e32 v134, v134
	v_exp_f32_e32 v135, v135
	v_mfma_f32_32x32x16_bf16 v[82:97], v[208:211], v[164:167], v[146:161]
	s_add_u32 s60, s50, 0xc0000
	s_addc_u32 s61, s51, 0
	s_mov_b32 s4, m0
	s_mov_b32 m0, s80
	s_nop 0
	global_load_lds_dwordx4 v250, s[60:61]
	s_mov_b32 m0, s4
	v_mfma_f32_32x32x16_bf16 v[98:113], v[212:215], v[168:171], v[98:113]
	s_add_u32 s60, s50, 0xc0080
	s_addc_u32 s61, s51, 0
	s_mov_b32 s4, m0
	s_mov_b32 m0, s83
	s_nop 0
	global_load_lds_dwordx4 v250, s[60:61]
	s_mov_b32 m0, s4
	v_exp_f32_e32 v136, v136
	v_exp_f32_e32 v137, v137
	v_exp_f32_e32 v138, v138
	v_mfma_f32_32x32x16_bf16 v[82:97], v[216:219], v[168:171], v[82:97]
	v_exp_f32_e32 v139, v139
	v_exp_f32_e32 v140, v140
	v_exp_f32_e32 v141, v141
	v_mfma_f32_32x32x16_bf16 v[98:113], v[220:223], v[172:175], v[98:113]
	v_exp_f32_e32 v142, v142
	ds_read_b64_tr_b16 v[4:5], v246 offset:40960
	ds_read_b64_tr_b16 v[6:7], v246 offset:41472
	v_exp_f32_e32 v143, v143
	v_exp_f32_e32 v144, v144
	v_cvt_pk_bf16_f32 v8, v130, v131
	v_cvt_pk_bf16_f32 v9, v132, v133
	v_cvt_pk_bf16_f32 v10, v134, v135
	v_cvt_pk_bf16_f32 v11, v136, v137
	v_mfma_f32_32x32x16_bf16 v[82:97], v[224:227], v[172:175], v[82:97]
	ds_read_b64_tr_b16 v[178:179], v246 offset:45056
	ds_read_b64_tr_b16 v[180:181], v246 offset:45568
	v_exp_f32_e32 v145, v145
	v_exp_f32_e32 v114, v114
	v_exp_f32_e32 v115, v115
	v_mfma_f32_32x32x16_bf16 v[98:113], v[228:231], v[236:239], v[98:113]
	ds_read_b64_tr_b16 v[182:183], v246 offset:49152
	ds_read_b64_tr_b16 v[184:185], v246 offset:49664
	v_exp_f32_e32 v116, v116
	v_exp_f32_e32 v117, v117
	v_exp_f32_e32 v118, v118
	v_cvt_pk_bf16_f32 v186, v138, v139
	v_cvt_pk_bf16_f32 v187, v140, v141
	v_cvt_pk_bf16_f32 v188, v142, v143
	v_cvt_pk_bf16_f32 v189, v144, v145
	v_mfma_f32_32x32x16_bf16 v[82:97], v[232:235], v[236:239], v[82:97]
	v_add_u32_e32 v240, s91, v249
	ds_read_b64_tr_b16 v[190:191], v246 offset:53248
	ds_read_b64_tr_b16 v[192:193], v246 offset:53760
	v_exp_f32_e32 v119, v119
	v_exp_f32_e32 v120, v120
	v_exp_f32_e32 v121, v121
	s_waitcnt lgkmcnt(6)
	v_mfma_f32_32x32x16_bf16 v[18:33], v[8:11], v[4:7], v[18:33]
	ds_read_b64_tr_b16 v[12:13], v246 offset:41984
	ds_read_b64_tr_b16 v[14:15], v246 offset:42496
	ds_read_b128 v[204:207], v240
	v_add_f32_e32 v194, v130, v131
	v_exp_f32_e32 v122, v122
	v_exp_f32_e32 v123, v123
	v_add_f32_e32 v194, v132, v194
	v_add_f32_e32 v4, v133, v194
	v_add_f32_e32 v4, v134, v4
	v_add_f32_e32 v194, v135, v4
	s_waitcnt lgkmcnt(7)
	v_mfma_f32_32x32x16_bf16 v[34:49], v[8:11], v[178:181], v[34:49]
	ds_read_b64_tr_b16 v[4:5], v246 offset:46080
	ds_read_b64_tr_b16 v[6:7], v246 offset:46592
	ds_read_b128 v[208:211], v240 offset:512
	v_exp_f32_e32 v124, v124
	v_exp_f32_e32 v125, v125
	v_add_f32_e32 v194, v136, v194
	v_add_f32_e32 v178, v137, v194
	v_add_f32_e32 v178, v138, v178
	v_add_f32_e32 v194, v139, v178
	s_waitcnt lgkmcnt(8)
	v_mfma_f32_32x32x16_bf16 v[50:65], v[8:11], v[182:185], v[50:65]
	ds_read_b64_tr_b16 v[178:179], v246 offset:50176
	ds_read_b64_tr_b16 v[180:181], v246 offset:50688
	ds_read_b128 v[212:215], v240 offset:2048
	v_exp_f32_e32 v126, v126
	v_exp_f32_e32 v127, v127
	v_add_f32_e32 v194, v140, v194
	v_add_f32_e32 v182, v141, v194
	v_add_f32_e32 v182, v142, v182
	v_add_f32_e32 v194, v143, v182
	s_waitcnt lgkmcnt(9)
	v_mfma_f32_32x32x16_bf16 v[66:81], v[8:11], v[190:193], v[66:81]
	ds_read_b64_tr_b16 v[182:183], v246 offset:54272
	ds_read_b64_tr_b16 v[184:185], v246 offset:54784
	ds_read_b128 v[216:219], v240 offset:2560
	v_exp_f32_e32 v128, v128
	v_exp_f32_e32 v129, v129
	v_add_f32_e32 v194, v144, v194
	v_add_f32_e32 v8, v145, v194
	v_add_f32_e32 v8, v114, v8
	v_add_f32_e32 v190, v115, v8
	s_waitcnt lgkmcnt(10)
	v_mfma_f32_32x32x16_bf16 v[18:33], v[186:189], v[12:15], v[18:33]
	ds_read_b64_tr_b16 v[8:9], v246 offset:43008
	ds_read_b64_tr_b16 v[10:11], v246 offset:43520
	ds_read_b128 v[220:223], v240 offset:4096
	v_add_f32_e32 v190, v116, v190
	v_add_f32_e32 v190, v117, v190
	v_add_f32_e32 v190, v118, v190
	v_add_f32_e32 v194, v119, v190
	v_cvt_pk_bf16_f32 v12, v114, v115
	v_cvt_pk_bf16_f32 v13, v116, v117
	v_cvt_pk_bf16_f32 v14, v118, v119
	v_cvt_pk_bf16_f32 v15, v120, v121
	s_waitcnt lgkmcnt(10)
	v_mfma_f32_32x32x16_bf16 v[34:49], v[186:189], v[4:7], v[34:49]
	ds_read_b64_tr_b16 v[190:191], v246 offset:47104
	ds_read_b64_tr_b16 v[192:193], v246 offset:47616
	ds_read_b128 v[224:227], v240 offset:4608
	v_add_f32_e32 v194, v120, v194
	v_add_f32_e32 v194, v121, v194
	v_add_f32_e32 v194, v122, v194
	v_add_f32_e32 v198, v123, v194
	v_cvt_pk_bf16_f32 v4, v122, v123
	v_cvt_pk_bf16_f32 v5, v124, v125
	v_cvt_pk_bf16_f32 v6, v126, v127
	v_cvt_pk_bf16_f32 v7, v128, v129
	s_waitcnt lgkmcnt(10)
	v_mfma_f32_32x32x16_bf16 v[50:65], v[186:189], v[178:181], v[50:65]
	ds_read_b64_tr_b16 v[194:195], v246 offset:51200
	ds_read_b64_tr_b16 v[196:197], v246 offset:51712
	ds_read_b128 v[228:231], v240 offset:6144
	v_add_f32_e32 v198, v124, v198
	v_add_f32_e32 v198, v125, v198
	v_add_f32_e32 v198, v126, v198
	v_add_f32_e32 v198, v127, v198
	s_waitcnt lgkmcnt(10)
	v_mfma_f32_32x32x16_bf16 v[66:81], v[186:189], v[182:185], v[66:81]
	ds_read_b64_tr_b16 v[178:179], v246 offset:55296
	ds_read_b64_tr_b16 v[180:181], v246 offset:55808
	ds_read_b128 v[232:235], v240 offset:6656
	v_add_f32_e32 v198, v128, v198
	v_add_f32_e32 v198, v129, v198
	v_add_f32_e32 v198, 0, v198
	s_waitcnt lgkmcnt(10)
	v_mfma_f32_32x32x16_bf16 v[18:33], v[12:15], v[8:11], v[18:33]
	ds_read_b64_tr_b16 v[182:183], v246 offset:44032
	ds_read_b64_tr_b16 v[184:185], v246 offset:44544
	s_cmpk_lt_u32 s86, 0x100
	s_cbranch_scc0 .Lattn_kdma_3
	s_add_i32 s4, s88, s84
	s_add_u32 s60, s58, 0x180000
	s_addc_u32 s61, s59, 0
	s_mov_b32 s5, m0
	s_mov_b32 m0, s4
	s_nop 0
	global_load_lds_dwordx4 v252, s[60:61]
	s_mov_b32 m0, s5
; __device__ __forceinline__ float max3f(float a,float b,float c){float r;asm("v_max3_f32 %0, %1, %2, %3":"=v"(r):"v"(a),"v"(b),"v"(c));return r;}
; __device__ __forceinline__ float max2f(float a,float b){float r;asm("v_max_f32_e32 %0, %1, %2":"=v"(r):"v"(a),"v"(b));return r;}
; #define EXP1(x) x=__builtin_amdgcn_exp2f((x)-mh_)
;   #define PINAB() asm volatile("":"+v"(ma),"+v"(mb))
; template<int THRL,bool FIRST> __device__ __forceinline__ void step_main(f32x16&p0,f32x16&p1,f32x16&n0,f32x16&n1,St&S,lds_cptr kpn,lds_cptr qp,lds_cptr vp,float*wsf,int r32,int hi,float&rm){
;     ...
;   PVG(0,pw0,vfa,4, p0[2],p0[3],p0[4],p0[5],   do{EXP1(p1[8]);EXP1(p1[9]);}while(0));
;   PVG(1,pw0,vfb,5, p0[6],p0[7],p0[8],p0[9], do{EXP1(p1[10]);EXP1(p1[11]);}while(0));
;   PVG(2,pw0,vfc,6, p0[10],p0[11],p0[12],p0[13], do{EXP1(p1[12]);EXP1(p1[13]);}while(0));
;   PVG(3,pw0,vfd,7, p0[14],p0[15],p1[0],p1[1],   do{EXP1(p1[14]);EXP1(p1[15]);}while(0));
;   PVG(4,pw1,vfa,8, p1[2],p1[3],p1[4],p1[5],   pw2=packw(p1,0));
;   PVG(5,pw1,vfb,9, p1[6],p1[7],p1[8],p1[9], pw3=packw(p1,8));
;   PVG(6,pw1,vfc,10, p1[10],p1[11],p1[12],p1[13], do{}while(0));
;   PVG(7,pw1,vfd,11, p1[14],p1[15],0.f,0.f, do{}while(0));
;   float ma,mb;
;     ...
;   PVG(8,pw2,vfa,12,0.f,0.f,0.f,0.f, do{ma=max3f(n0[0],n0[1],n1[0]);mb=max3f(n0[2],n0[3],n1[1]);PINAB();}while(0));
;   PVG(9,pw2,vfb,13,0.f,0.f,0.f,0.f, do{ma=max3f(ma,n1[2],n1[3]);mb=max3f(mb,n0[4],n0[5]);PINAB();}while(0));
;   PVG(10,pw2,vfc,14,0.f,0.f,0.f,0.f, do{ma=max3f(ma,n0[6],n0[7]);mb=max3f(mb,n1[4],n1[5]);PINAB();}while(0));
;   PVG(11,pw2,vfd,15,0.f,0.f,0.f,0.f, do{ma=max3f(ma,n1[6],n1[7]);mb=max3f(mb,n0[8],n0[9]);PINAB();}while(0));
;   PVG(12,pw3,vfa,16,0.f,0.f,0.f,0.f, do{ma=max3f(ma,n0[10],n0[11]);mb=max3f(mb,n1[8],n1[9]);PINAB();}while(0));
;   PVG(13,pw3,vfb,16,0.f,0.f,0.f,0.f, do{ma=max3f(ma,n1[10],n1[11]);mb=max3f(mb,n0[12],n0[13]);PINAB();}while(0));
;   PVG(14,pw3,vfc,16,0.f,0.f,0.f,0.f, do{ma=max3f(ma,n0[14],n0[15]);mb=max3f(mb,n1[12],n1[13]);PINAB();}while(0));
;   PVG(15,pw3,vfd,16,0.f,0.f,0.f,0.f, do{ma=max3f(ma,n1[14],n1[15]);ma=max2f(ma,mb);PINAB();}while(0));
;     ...
;   { auto rr=__builtin_amdgcn_permlane32_swap(__float_as_uint(ma),__float_as_uint(ma),false,false); rm=max2f(__uint_as_float(rr[0]),__uint_as_float(rr[1])); }
;     ...
;   S.l_reg+=sa;
.Lattn_kdma_3:
	v_max3_f32 v186, v98, v99, v82
	v_max3_f32 v187, v100, v101, v83
	s_nop 0
	s_waitcnt lgkmcnt(9)
	v_mfma_f32_32x32x16_bf16 v[34:49], v[12:15], v[190:193], v[34:49]
	ds_read_b64_tr_b16 v[8:9], v246 offset:48128
	ds_read_b64_tr_b16 v[10:11], v246 offset:48640
	v_max3_f32 v199, v186, v84, v85
	v_max3_f32 v200, v187, v102, v103
	s_nop 0
	s_waitcnt lgkmcnt(8)
	v_mfma_f32_32x32x16_bf16 v[50:65], v[12:15], v[194:197], v[50:65]
	ds_read_b64_tr_b16 v[186:187], v246 offset:52224
	ds_read_b64_tr_b16 v[188:189], v246 offset:52736
	v_max3_f32 v199, v199, v104, v105
	v_max3_f32 v200, v200, v86, v87
	s_nop 0
	s_waitcnt lgkmcnt(7)
	v_mfma_f32_32x32x16_bf16 v[66:81], v[12:15], v[178:181], v[66:81]
	ds_read_b64_tr_b16 v[190:191], v246 offset:56320
	ds_read_b64_tr_b16 v[192:193], v246 offset:56832
	v_max3_f32 v194, v199, v88, v89
	v_max3_f32 v195, v200, v106, v107
	s_nop 0
	s_waitcnt lgkmcnt(6)
	v_mfma_f32_32x32x16_bf16 v[18:33], v[4:7], v[182:185], v[18:33]
	s_cmpk_lt_u32 s86, 0x100
	s_cbranch_scc1 .Lattn_kdma_4
	s_add_i32 s4, s88, s84
	s_add_u32 s60, s58, 0x180000
	s_addc_u32 s61, s59, 0
	s_mov_b32 s5, m0
	s_mov_b32 m0, s4
	s_nop 0
	global_load_lds_dwordx4 v252, s[60:61]
	s_mov_b32 m0, s5
.Lattn_kdma_4:
	s_add_i32 s4, s91, 0x2000
	s_cmpk_lg_i32 s91, 0x4000
	s_cselect_b32 s88, s4, 0
	v_max3_f32 v12, v194, v108, v109
	v_max3_f32 v13, v195, v90, v91
	s_nop 0
	s_waitcnt lgkmcnt(4)
	v_mfma_f32_32x32x16_bf16 v[34:49], v[4:7], v[8:11], v[34:49]
	v_max3_f32 v12, v12, v92, v93
	v_max3_f32 v13, v13, v110, v111
	s_nop 0
	s_waitcnt lgkmcnt(2)
	v_mfma_f32_32x32x16_bf16 v[50:65], v[4:7], v[186:189], v[50:65]
	v_max3_f32 v8, v12, v112, v113
	v_max3_f32 v9, v13, v94, v95
	s_nop 0
	s_waitcnt lgkmcnt(0)
	v_mfma_f32_32x32x16_bf16 v[66:81], v[4:7], v[190:193], v[66:81]
	v_max3_f32 v8, v8, v96, v97
	s_nop 0
	v_max_f32_e32 v8, v8, v9
	s_nop 0
	s_add_u32 s58, s58, 0x180000
	s_addc_u32 s59, s59, 0
	s_add_u32 s50, s50, 0x180000
	s_waitcnt vmcnt(1) lgkmcnt(0)
	s_barrier
	s_addc_u32 s51, s51, 0
	v_mov_b32_e32 v4, v8
	v_add_f32_e32 v251, v17, v198
	s_cmp_lt_u32 s90, s89
	v_permlane32_swap_b32_e32 v8, v4
	v_max_f32_e32 v178, v8, v4
	s_cbranch_scc0 .LBB0_285

; #define SB() __builtin_amdgcn_sched_barrier(0)
; #define MF32(a,b,c) __builtin_amdgcn_mfma_f32_32x32x16_bf16(a,b,c,0,0,0)
; #define EXP1(x) x=__builtin_amdgcn_exp2f((x)-mh_)
; __device__ __forceinline__ bf16x8 vfrag(lds_cptr vp,int i){ const s16x4 lo=vtr(vp+(i&3)*4096+(i>>2)*1024), hh=vtr(vp+(i&3)*4096+(i>>2)*1024+512); return (bf16x8){lo[0],lo[1],lo[2],lo[3],hh[0],hh[1],hh[2],hh[3]}; }
; __device__ __forceinline__ u32x4 packw(const f32x16&p,int base){ u32x4 w; w[0]=cvtpk_s(p[base],p[base+1]); w[1]=cvtpk_s(p[base+2],p[base+3]); w[2]=cvtpk_s(p[base+4],p[base+5]); w[3]=cvtpk_s(p[base+6],p[base+7]); return w; }
; template<int THRL,bool FIRST> __device__ __forceinline__ void step_main(f32x16&p0,f32x16&p1,f32x16&n0,f32x16&n1,St&S,lds_cptr kpn,lds_cptr qp,lds_cptr vp,float*wsf,int r32,int hi,float&rm){
;     ...
;   bf16x8 ka=KF(0),kb=KF(1),kc=KF(2),kd=KF(3),qa=QF(0),qb=QF(1);
;   decide<THRL,FIRST>(rm,S,wsf,r32,hi);
;   u32x4 pw0,pw1,pw2,pw3; const float mh_=S.mhat; const f32x16 z=f32x16{};
;   SB();
;   n0=MF32(ka,qa,z); ka=KF(4); EXP1(p0[0]);EXP1(p0[1]);EXP1(p0[2]); SB();
;   n1=MF32(kb,qa,z); kb=KF(5); qa=QF(2); EXP1(p0[3]);EXP1(p0[4]);EXP1(p0[5]); SB();
;   n0=MF32(kc,qb,n0);   kc=KF(6); EXP1(p0[6]);EXP1(p0[7]);EXP1(p0[8]); SB();
;   n1=MF32(kd,qb,n1);   kd=KF(7); qb=QF(3); EXP1(p0[9]);EXP1(p0[10]);EXP1(p0[11]); SB();
;   bf16x8 vfa=vfrag(vp,0);
;   n0=MF32(ka,qa,n0);   EXP1(p0[12]);EXP1(p0[13]);EXP1(p0[14]); pw0=packw(p0,0); SB();
;   bf16x8 vfb=vfrag(vp,1);
;   n1=MF32(kb,qa,n1);   EXP1(p0[15]);EXP1(p1[0]);EXP1(p1[1]); SB();
;   bf16x8 vfc=vfrag(vp,2);
;   n0=MF32(kc,qb,n0);   EXP1(p1[2]);EXP1(p1[3]);EXP1(p1[4]); pw1=packw(p0,8); SB();
;   bf16x8 vfd=vfrag(vp,3);
;   n1=MF32(kd,qb,n1);   EXP1(p1[5]);EXP1(p1[6]);EXP1(p1[7]); SB();
;     ...
;   float sa=p0[0]+p0[1];
;     ...
;   PVG(0,pw0,vfa,4, p0[2],p0[3],p0[4],p0[5],   do{EXP1(p1[8]);EXP1(p1[9]);}while(0));
;   PVG(1,pw0,vfb,5, p0[6],p0[7],p0[8],p0[9], do{EXP1(p1[10]);EXP1(p1[11]);}while(0));
;   PVG(2,pw0,vfc,6, p0[10],p0[11],p0[12],p0[13], do{EXP1(p1[12]);EXP1(p1[13]);}while(0));
;   PVG(3,pw0,vfd,7, p0[14],p0[15],p1[0],p1[1],   do{EXP1(p1[14]);EXP1(p1[15]);}while(0));
;   PVG(4,pw1,vfa,8, p1[2],p1[3],p1[4],p1[5],   pw2=packw(p1,0));
;   PVG(5,pw1,vfb,9, p1[6],p1[7],p1[8],p1[9], pw3=packw(p1,8));
;   PVG(6,pw1,vfc,10, p1[10],p1[11],p1[12],p1[13], do{}while(0));
;   PVG(7,pw1,vfd,11, p1[14],p1[15],0.f,0.f, do{}while(0));
.LBB0_282:
	v_mfma_f32_32x32x16_bf16 v[130:145], v[204:207], v[164:167], v[146:161]
	v_exp_f32_e32 v190, v98
	v_exp_f32_e32 v191, v99
	v_exp_f32_e32 v192, v100
	v_mfma_f32_32x32x16_bf16 v[114:129], v[208:211], v[164:167], v[146:161]
	s_mov_b32 s4, m0
	s_mov_b32 m0, s79
	s_nop 0
	global_load_lds_dwordx4 v250, s[50:51]
	s_mov_b32 m0, s4
	v_exp_f32_e32 v193, v101
	v_exp_f32_e32 v194, v102
	v_exp_f32_e32 v195, v103
	v_mfma_f32_32x32x16_bf16 v[130:145], v[212:215], v[168:171], v[130:145]
	s_add_u32 s60, s50, 0x80
	s_addc_u32 s61, s51, 0
	s_mov_b32 s4, m0
	s_mov_b32 m0, s41
	s_nop 0
	global_load_lds_dwordx4 v250, s[60:61]
	s_mov_b32 m0, s4
	v_exp_f32_e32 v196, v104
	v_exp_f32_e32 v197, v105
	v_exp_f32_e32 v198, v106
	v_mfma_f32_32x32x16_bf16 v[114:129], v[216:219], v[168:171], v[114:129]
	v_exp_f32_e32 v17, v107
	v_exp_f32_e32 v199, v108
	v_exp_f32_e32 v200, v109
	v_mfma_f32_32x32x16_bf16 v[130:145], v[220:223], v[172:175], v[130:145]
	v_exp_f32_e32 v201, v110
	ds_read_b64_tr_b16 v[4:5], v246 offset:24576
	ds_read_b64_tr_b16 v[6:7], v246 offset:25088
	v_exp_f32_e32 v202, v111
	v_exp_f32_e32 v178, v112
	v_cvt_pk_bf16_f32 v8, v190, v191
	v_cvt_pk_bf16_f32 v9, v192, v193
	v_cvt_pk_bf16_f32 v10, v194, v195
	v_cvt_pk_bf16_f32 v11, v196, v197
	v_mfma_f32_32x32x16_bf16 v[114:129], v[224:227], v[172:175], v[114:129]
	ds_read_b64_tr_b16 v[106:107], v246 offset:28672
	ds_read_b64_tr_b16 v[108:109], v246 offset:29184
	v_exp_f32_e32 v180, v82
	v_exp_f32_e32 v179, v113
	v_exp_f32_e32 v181, v83
	v_mfma_f32_32x32x16_bf16 v[130:145], v[228:231], v[236:239], v[130:145]
	ds_read_b64_tr_b16 v[110:111], v246 offset:32768
	ds_read_b64_tr_b16 v[112:113], v246 offset:33280
	v_exp_f32_e32 v182, v84
	v_exp_f32_e32 v183, v85
	v_exp_f32_e32 v184, v86
	v_cvt_pk_bf16_f32 v82, v198, v17
	v_cvt_pk_bf16_f32 v83, v199, v200
	v_cvt_pk_bf16_f32 v84, v201, v202
	v_cvt_pk_bf16_f32 v85, v178, v179
	v_mfma_f32_32x32x16_bf16 v[114:129], v[232:235], v[236:239], v[114:129]
	v_add_u32_e32 v240, s88, v249
	ds_read_b64_tr_b16 v[98:99], v246 offset:36864
	ds_read_b64_tr_b16 v[100:101], v246 offset:37376
	v_exp_f32_e32 v185, v87
	v_exp_f32_e32 v186, v88
	v_exp_f32_e32 v187, v89
	s_waitcnt lgkmcnt(6)
	v_mfma_f32_32x32x16_bf16 v[18:33], v[8:11], v[4:7], v[18:33]
	ds_read_b128 v[204:207], v240
	v_add_f32_e32 v86, v190, v191
	ds_read_b64_tr_b16 v[12:13], v246 offset:25600
	ds_read_b64_tr_b16 v[14:15], v246 offset:26112
	v_add_f32_e32 v86, v192, v86
	v_exp_f32_e32 v103, v91
	v_add_f32_e32 v4, v193, v86
	v_add_f32_e32 v4, v194, v4
	v_add_f32_e32 v86, v195, v4
	v_exp_f32_e32 v102, v90
	s_waitcnt lgkmcnt(7)
	v_mfma_f32_32x32x16_bf16 v[34:49], v[8:11], v[106:109], v[34:49]
	ds_read_b64_tr_b16 v[4:5], v246 offset:29696
	ds_read_b64_tr_b16 v[6:7], v246 offset:30208
	ds_read_b128 v[208:211], v240 offset:512
	v_add_f32_e32 v86, v196, v86
	v_add_f32_e32 v86, v197, v86
	v_add_f32_e32 v86, v198, v86
	v_exp_f32_e32 v104, v92
	v_add_f32_e32 v17, v17, v86
	v_exp_f32_e32 v105, v93
	s_waitcnt lgkmcnt(8)
	v_mfma_f32_32x32x16_bf16 v[50:65], v[8:11], v[110:113], v[50:65]
	ds_read_b64_tr_b16 v[86:87], v246 offset:33792
	ds_read_b64_tr_b16 v[88:89], v246 offset:34304
	ds_read_b128 v[212:215], v240 offset:2048
	v_add_f32_e32 v17, v199, v17
	v_add_f32_e32 v17, v200, v17
	v_add_f32_e32 v17, v201, v17
	v_exp_f32_e32 v106, v94
	v_add_f32_e32 v17, v202, v17
	v_exp_f32_e32 v107, v95
	s_waitcnt lgkmcnt(9)
	v_mfma_f32_32x32x16_bf16 v[66:81], v[8:11], v[98:101], v[66:81]
	ds_read_b64_tr_b16 v[90:91], v246 offset:37888
	ds_read_b64_tr_b16 v[92:93], v246 offset:38400
	ds_read_b128 v[216:219], v240 offset:2560
	v_add_f32_e32 v17, v178, v17
	v_add_f32_e32 v8, v179, v17
	v_add_f32_e32 v8, v180, v8
	v_exp_f32_e32 v108, v96
	v_add_f32_e32 v17, v181, v8
	v_exp_f32_e32 v109, v97
	s_waitcnt lgkmcnt(9)
	v_mfma_f32_32x32x16_bf16 v[18:33], v[82:85], v[12:15], v[18:33]
	ds_read_b64_tr_b16 v[8:9], v246 offset:26624
	ds_read_b64_tr_b16 v[10:11], v246 offset:27136
	ds_read_b128 v[220:223], v240 offset:4096
	v_add_f32_e32 v17, v182, v17
	v_add_f32_e32 v17, v183, v17
	v_add_f32_e32 v17, v184, v17
	v_add_f32_e32 v17, v185, v17
	v_cvt_pk_bf16_f32 v12, v180, v181
	v_cvt_pk_bf16_f32 v13, v182, v183
	v_cvt_pk_bf16_f32 v14, v184, v185
	v_cvt_pk_bf16_f32 v15, v186, v187
	s_waitcnt lgkmcnt(10)
	v_mfma_f32_32x32x16_bf16 v[34:49], v[82:85], v[4:7], v[34:49]
	ds_read_b64_tr_b16 v[94:95], v246 offset:30720
	ds_read_b64_tr_b16 v[96:97], v246 offset:31232
	ds_read_b128 v[224:227], v240 offset:4608
	v_add_f32_e32 v17, v186, v17
	v_add_f32_e32 v17, v187, v17
	v_add_f32_e32 v17, v102, v17
	v_add_f32_e32 v17, v103, v17
	v_cvt_pk_bf16_f32 v4, v102, v103
	v_cvt_pk_bf16_f32 v5, v104, v105
	v_cvt_pk_bf16_f32 v6, v106, v107
	v_cvt_pk_bf16_f32 v7, v108, v109
	s_waitcnt lgkmcnt(10)
	v_mfma_f32_32x32x16_bf16 v[50:65], v[82:85], v[86:89], v[50:65]
	ds_read_b64_tr_b16 v[98:99], v246 offset:34816
	ds_read_b64_tr_b16 v[100:101], v246 offset:35328
	ds_read_b128 v[228:231], v240 offset:6144
	v_add_f32_e32 v17, v104, v17
	v_add_f32_e32 v17, v105, v17
	v_add_f32_e32 v17, v106, v17
	v_add_f32_e32 v17, v107, v17
	s_waitcnt lgkmcnt(10)
	v_mfma_f32_32x32x16_bf16 v[66:81], v[82:85], v[90:93], v[66:81]
	ds_read_b64_tr_b16 v[86:87], v246 offset:38912
	ds_read_b64_tr_b16 v[88:89], v246 offset:39424
	ds_read_b128 v[232:235], v240 offset:6656
	v_add_f32_e32 v17, v108, v17
	v_add_f32_e32 v17, v109, v17
	v_add_f32_e32 v17, 0, v17
	s_waitcnt lgkmcnt(10)
	v_mfma_f32_32x32x16_bf16 v[18:33], v[12:15], v[8:11], v[18:33]
	ds_read_b64_tr_b16 v[82:83], v246 offset:27648
	ds_read_b64_tr_b16 v[84:85], v246 offset:28160
	s_cmpk_lt_u32 s86, 0x100
	s_cbranch_scc0 .Lattn_kdma_1
	s_add_i32 s4, s91, s84
	s_add_u32 s60, s58, 0xc0000
	s_addc_u32 s61, s59, 0
	s_mov_b32 s5, m0
	s_mov_b32 m0, s4
	s_nop 0
	global_load_lds_dwordx4 v252, s[60:61]
	s_mov_b32 m0, s5
; __device__ __forceinline__ int crow(int r,int hi){return (r&3)+8*(r>>2)+4*hi;}
; __device__ __forceinline__ float max3f(float a,float b,float c){float r;asm("v_max3_f32 %0, %1, %2, %3":"=v"(r):"v"(a),"v"(b),"v"(c));return r;}
; __device__ __forceinline__ float max2f(float a,float b){float r;asm("v_max_f32_e32 %0, %1, %2":"=v"(r):"v"(a),"v"(b));return r;}
;   #define PVG(i,PW,VF,NEXTI,X0,X1,Y0,Y1,EXTRA) do{ S.o[(i)&3]=MF32(__builtin_bit_cast(bf16x8,PW),VF,S.o[(i)&3]); if((NEXTI)<16){ VF=vfrag(vp,(NEXTI)<16?(NEXTI):0); } sa+=X0; sa+=X1; sa+=Y0; sa+=Y1; EXTRA; SB(); }while(0)
; template<int THRL,bool FIRST> __device__ __forceinline__ void decide(float rm,St&S,float*wsf,int r32,int hi){
;     ...
;   else if(__any(rm-S.mhat>(float)THRL)){
;     const float dl=__builtin_fmaxf(rm-S.mhat,0.f); S.mhat+=dl;
;     const float f=__builtin_amdgcn_exp2f(-dl); S.l_reg*=f; if(hi==0)wsf[r32]=f;
;     asm volatile("s_waitcnt lgkmcnt(0)":::"memory");
;     #pragma unroll
;     for(int r=0;r<16;++r){ const float fr=wsf[crow(r,hi)];
;       #pragma unroll
;       for(int d=0;d<4;++d)S.o[d][r]*=fr; }
; template<int THRL,bool FIRST> __device__ __forceinline__ void step_main(f32x16&p0,f32x16&p1,f32x16&n0,f32x16&n1,St&S,lds_cptr kpn,lds_cptr qp,lds_cptr vp,float*wsf,int r32,int hi,float&rm){
;     ...
;   float ma,mb;
;     ...
;   PVG(8,pw2,vfa,12,0.f,0.f,0.f,0.f, do{ma=max3f(n0[0],n0[1],n1[0]);mb=max3f(n0[2],n0[3],n1[1]);PINAB();}while(0));
;   PVG(9,pw2,vfb,13,0.f,0.f,0.f,0.f, do{ma=max3f(ma,n1[2],n1[3]);mb=max3f(mb,n0[4],n0[5]);PINAB();}while(0));
;   PVG(10,pw2,vfc,14,0.f,0.f,0.f,0.f, do{ma=max3f(ma,n0[6],n0[7]);mb=max3f(mb,n1[4],n1[5]);PINAB();}while(0));
;   PVG(11,pw2,vfd,15,0.f,0.f,0.f,0.f, do{ma=max3f(ma,n1[6],n1[7]);mb=max3f(mb,n0[8],n0[9]);PINAB();}while(0));
;   PVG(12,pw3,vfa,16,0.f,0.f,0.f,0.f, do{ma=max3f(ma,n0[10],n0[11]);mb=max3f(mb,n1[8],n1[9]);PINAB();}while(0));
;   PVG(13,pw3,vfb,16,0.f,0.f,0.f,0.f, do{ma=max3f(ma,n1[10],n1[11]);mb=max3f(mb,n0[12],n0[13]);PINAB();}while(0));
;   PVG(14,pw3,vfc,16,0.f,0.f,0.f,0.f, do{ma=max3f(ma,n0[14],n0[15]);mb=max3f(mb,n1[12],n1[13]);PINAB();}while(0));
;   PVG(15,pw3,vfd,16,0.f,0.f,0.f,0.f, do{ma=max3f(ma,n1[14],n1[15]);ma=max2f(ma,mb);PINAB();}while(0));
;     ...
;   { auto rr=__builtin_amdgcn_permlane32_swap(__float_as_uint(ma),__float_as_uint(ma),false,false); rm=max2f(__uint_as_float(rr[0]),__uint_as_float(rr[1])); }
.Lattn_kdma_1:
	v_max3_f32 v90, v130, v131, v114
	v_max3_f32 v91, v132, v133, v115
	s_nop 0
	s_waitcnt lgkmcnt(9)
	v_mfma_f32_32x32x16_bf16 v[34:49], v[12:15], v[94:97], v[34:49]
	ds_read_b64_tr_b16 v[8:9], v246 offset:31744
	ds_read_b64_tr_b16 v[10:11], v246 offset:32256
	v_max3_f32 v102, v90, v116, v117
	v_max3_f32 v103, v91, v134, v135
	s_nop 0
	s_waitcnt lgkmcnt(8)
	v_mfma_f32_32x32x16_bf16 v[50:65], v[12:15], v[98:101], v[50:65]
	ds_read_b64_tr_b16 v[90:91], v246 offset:35840
	ds_read_b64_tr_b16 v[92:93], v246 offset:36352
	v_max3_f32 v102, v102, v136, v137
	v_max3_f32 v103, v103, v118, v119
	s_nop 0
	s_waitcnt lgkmcnt(7)
	v_mfma_f32_32x32x16_bf16 v[66:81], v[12:15], v[86:89], v[66:81]
	ds_read_b64_tr_b16 v[94:95], v246 offset:39936
	ds_read_b64_tr_b16 v[96:97], v246 offset:40448
	v_max3_f32 v98, v102, v120, v121
	v_max3_f32 v99, v103, v138, v139
	s_nop 0
	s_waitcnt lgkmcnt(6)
	v_mfma_f32_32x32x16_bf16 v[18:33], v[4:7], v[82:85], v[18:33]
	s_cmpk_lt_u32 s86, 0x100
	s_cbranch_scc1 .Lattn_kdma_2
	s_add_i32 s4, s91, s84
	s_add_u32 s60, s58, 0xc0000
	s_addc_u32 s61, s59, 0
	s_mov_b32 s5, m0
	s_mov_b32 m0, s4
	s_nop 0
	global_load_lds_dwordx4 v252, s[60:61]
	s_mov_b32 m0, s5
.Lattn_kdma_2:
	s_add_i32 s4, s88, 0x2000
	s_cmpk_lg_i32 s88, 0x4000
	s_cselect_b32 s91, s4, 0
	v_max3_f32 v12, v98, v140, v141
	v_max3_f32 v13, v99, v122, v123
	s_nop 0
	s_waitcnt lgkmcnt(4)
	v_mfma_f32_32x32x16_bf16 v[34:49], v[4:7], v[8:11], v[34:49]
	v_max3_f32 v12, v12, v124, v125
	v_max3_f32 v13, v13, v142, v143
	s_nop 0
	s_waitcnt lgkmcnt(2)
	v_mfma_f32_32x32x16_bf16 v[50:65], v[4:7], v[90:93], v[50:65]
	v_max3_f32 v8, v12, v144, v145
	v_max3_f32 v9, v13, v126, v127
	s_nop 0
	s_waitcnt lgkmcnt(0)
	v_mfma_f32_32x32x16_bf16 v[66:81], v[4:7], v[94:97], v[66:81]
	v_max3_f32 v8, v8, v128, v129
	s_nop 0
	v_max_f32_e32 v8, v8, v9
	s_nop 0
	v_mov_b32_e32 v162, v8
	v_mov_b32_e32 v163, v8
	s_waitcnt vmcnt(1) lgkmcnt(0)
	s_barrier
	v_permlane32_swap_b32_e32 v162, v163
	v_max_f32_e32 v94, v162, v163
	v_add_f32_e32 v17, v251, v17
	v_cmp_lt_f32_e32 vcc, s69, v94
	s_cbranch_vccz .LBB0_277
	v_max_f32_e32 v94, v94, v94
	v_max_f32_e32 v94, 0, v94
	v_exp_f32_e64 v95, -v94
	s_and_saveexec_b64 s[60:61], s[6:7]
	s_cbranch_execz .LBB0_276
	ds_write_b32 v16, v95
	s_branch .LBB0_276

; #define SB() __builtin_amdgcn_sched_barrier(0)
; #define MF32(a,b,c) __builtin_amdgcn_mfma_f32_32x32x16_bf16(a,b,c,0,0,0)
; #define EXP1(x) x=__builtin_amdgcn_exp2f((x)-mh_)
; __device__ __forceinline__ bf16x8 vfrag(lds_cptr vp,int i){ const s16x4 lo=vtr(vp+(i&3)*4096+(i>>2)*1024), hh=vtr(vp+(i&3)*4096+(i>>2)*1024+512); return (bf16x8){lo[0],lo[1],lo[2],lo[3],hh[0],hh[1],hh[2],hh[3]}; }
; __device__ __forceinline__ u32x4 packw(const f32x16&p,int base){ u32x4 w; w[0]=cvtpk_s(p[base],p[base+1]); w[1]=cvtpk_s(p[base+2],p[base+3]); w[2]=cvtpk_s(p[base+4],p[base+5]); w[3]=cvtpk_s(p[base+6],p[base+7]); return w; }
; template<int THRL,bool FIRST> __device__ __forceinline__ void step_main(f32x16&p0,f32x16&p1,f32x16&n0,f32x16&n1,St&S,lds_cptr kpn,lds_cptr qp,lds_cptr vp,float*wsf,int r32,int hi,float&rm){
;     ...
;   bf16x8 ka=KF(0),kb=KF(1),kc=KF(2),kd=KF(3),qa=QF(0),qb=QF(1);
;   decide<THRL,FIRST>(rm,S,wsf,r32,hi);
;   u32x4 pw0,pw1,pw2,pw3; const float mh_=S.mhat; const f32x16 z=f32x16{};
;   SB();
;   n0=MF32(ka,qa,z); ka=KF(4); EXP1(p0[0]);EXP1(p0[1]);EXP1(p0[2]); SB();
;   n1=MF32(kb,qa,z); kb=KF(5); qa=QF(2); EXP1(p0[3]);EXP1(p0[4]);EXP1(p0[5]); SB();
;   n0=MF32(kc,qb,n0);   kc=KF(6); EXP1(p0[6]);EXP1(p0[7]);EXP1(p0[8]); SB();
;   n1=MF32(kd,qb,n1);   kd=KF(7); qb=QF(3); EXP1(p0[9]);EXP1(p0[10]);EXP1(p0[11]); SB();
;   bf16x8 vfa=vfrag(vp,0);
;   n0=MF32(ka,qa,n0);   EXP1(p0[12]);EXP1(p0[13]);EXP1(p0[14]); pw0=packw(p0,0); SB();
;   bf16x8 vfb=vfrag(vp,1);
;   n1=MF32(kb,qa,n1);   EXP1(p0[15]);EXP1(p1[0]);EXP1(p1[1]); SB();
;   bf16x8 vfc=vfrag(vp,2);
;   n0=MF32(kc,qb,n0);   EXP1(p1[2]);EXP1(p1[3]);EXP1(p1[4]); pw1=packw(p0,8); SB();
;   bf16x8 vfd=vfrag(vp,3);
;   n1=MF32(kd,qb,n1);   EXP1(p1[5]);EXP1(p1[6]);EXP1(p1[7]); SB();
;     ...
;   float sa=p0[0]+p0[1];
;     ...
;   PVG(0,pw0,vfa,4, p0[2],p0[3],p0[4],p0[5],   do{EXP1(p1[8]);EXP1(p1[9]);}while(0));
;   PVG(1,pw0,vfb,5, p0[6],p0[7],p0[8],p0[9], do{EXP1(p1[10]);EXP1(p1[11]);}while(0));
;   PVG(2,pw0,vfc,6, p0[10],p0[11],p0[12],p0[13], do{EXP1(p1[12]);EXP1(p1[13]);}while(0));
;   PVG(3,pw0,vfd,7, p0[14],p0[15],p1[0],p1[1],   do{EXP1(p1[14]);EXP1(p1[15]);}while(0));
;   PVG(4,pw1,vfa,8, p1[2],p1[3],p1[4],p1[5],   pw2=packw(p1,0));
;   PVG(5,pw1,vfb,9, p1[6],p1[7],p1[8],p1[9], pw3=packw(p1,8));
;   PVG(6,pw1,vfc,10, p1[10],p1[11],p1[12],p1[13], do{}while(0));
;   PVG(7,pw1,vfd,11, p1[14],p1[15],0.f,0.f, do{}while(0));
.LBB0_433:
	s_waitcnt lgkmcnt(1)
	v_mfma_f32_32x32x16_bf16 v[98:113], v[218:221], v[214:217], 0
	ds_read_b128 v[178:181], v249 offset:20480
	v_sub_f32_e32 v82, v131, v247
	v_sub_f32_e32 v17, v130, v247
	v_exp_f32_e32 v190, v82
	v_sub_f32_e32 v82, v132, v247
	v_exp_f32_e32 v17, v17
	v_exp_f32_e32 v191, v82
	v_sub_f32_e32 v82, v133, v247
	v_exp_f32_e32 v192, v82
	v_sub_f32_e32 v82, v134, v247
	v_exp_f32_e32 v193, v82
	v_sub_f32_e32 v82, v135, v247
	v_exp_f32_e32 v194, v82
	v_mfma_f32_32x32x16_bf16 v[82:97], v[210:213], v[214:217], 0
	ds_read_b128 v[182:185], v249 offset:20992
	ds_read_b128 v[186:189], v248 offset:2048
	s_waitcnt lgkmcnt(3)
	v_mfma_f32_32x32x16_bf16 v[98:113], v[12:15], v[8:11], v[98:113]
	ds_read_b128 v[130:133], v249 offset:22528
	v_sub_f32_e32 v134, v136, v247
	v_exp_f32_e32 v195, v134
	v_sub_f32_e32 v134, v137, v247
	v_exp_f32_e32 v196, v134
	v_sub_f32_e32 v134, v138, v247
	v_exp_f32_e32 v197, v134
	v_mfma_f32_32x32x16_bf16 v[82:97], v[4:7], v[8:11], v[82:97]
	ds_read_b128 v[12:15], v249 offset:23040
	ds_read_b128 v[134:137], v248 offset:3072
	v_sub_f32_e32 v138, v139, v247
	v_exp_f32_e32 v198, v138
	v_sub_f32_e32 v138, v140, v247
	v_exp_f32_e32 v199, v138
	v_sub_f32_e32 v138, v141, v247
	v_exp_f32_e32 v200, v138
	s_waitcnt lgkmcnt(3)
	v_mfma_f32_32x32x16_bf16 v[98:113], v[178:181], v[186:189], v[98:113]
	ds_read_b64_tr_b16 v[4:5], v246 offset:40960
	ds_read_b64_tr_b16 v[6:7], v246 offset:41472
	v_sub_f32_e32 v8, v142, v247
	v_exp_f32_e32 v201, v8
	v_sub_f32_e32 v8, v143, v247
	v_exp_f32_e32 v202, v8
	v_sub_f32_e32 v8, v144, v247
	v_exp_f32_e32 v179, v8
	v_cvt_pk_bf16_f32 v8, v17, v190
	v_cvt_pk_bf16_f32 v9, v191, v192
	v_cvt_pk_bf16_f32 v10, v193, v194
	v_cvt_pk_bf16_f32 v11, v195, v196
	v_mfma_f32_32x32x16_bf16 v[82:97], v[182:185], v[186:189], v[82:97]
	ds_read_b64_tr_b16 v[138:139], v246 offset:45056
	ds_read_b64_tr_b16 v[140:141], v246 offset:45568
	v_sub_f32_e32 v114, v114, v247
	v_sub_f32_e32 v142, v145, v247
	v_exp_f32_e32 v181, v114
	v_sub_f32_e32 v114, v115, v247
	v_exp_f32_e32 v180, v142
	v_exp_f32_e32 v203, v114
	s_waitcnt lgkmcnt(4)
	v_mfma_f32_32x32x16_bf16 v[98:113], v[130:133], v[134:137], v[98:113]
	ds_read_b64_tr_b16 v[142:143], v246 offset:49152
	ds_read_b64_tr_b16 v[144:145], v246 offset:49664
	v_sub_f32_e32 v114, v116, v247
	v_exp_f32_e32 v182, v114
	v_sub_f32_e32 v114, v117, v247
	v_exp_f32_e32 v183, v114
	v_sub_f32_e32 v114, v118, v247
	v_exp_f32_e32 v184, v114
	v_cvt_pk_bf16_f32 v114, v197, v198
	v_cvt_pk_bf16_f32 v115, v199, v200
	v_cvt_pk_bf16_f32 v116, v201, v202
	v_cvt_pk_bf16_f32 v117, v179, v180
	v_mfma_f32_32x32x16_bf16 v[82:97], v[12:15], v[134:137], v[82:97]
	ds_read_b64_tr_b16 v[130:131], v246 offset:53248
	ds_read_b64_tr_b16 v[132:133], v246 offset:53760
	v_sub_f32_e32 v118, v119, v247
	v_exp_f32_e32 v185, v118
	v_sub_f32_e32 v118, v120, v247
	v_exp_f32_e32 v186, v118
	v_sub_f32_e32 v118, v121, v247
	v_exp_f32_e32 v187, v118
	s_waitcnt lgkmcnt(6)
	v_mfma_f32_32x32x16_bf16 v[18:33], v[8:11], v[4:7], v[18:33]
	ds_read_b64_tr_b16 v[12:13], v246 offset:41984
	ds_read_b64_tr_b16 v[14:15], v246 offset:42496
	v_sub_f32_e32 v118, v122, v247
	v_exp_f32_e32 v134, v118
	v_sub_f32_e32 v118, v123, v247
	v_exp_f32_e32 v135, v118
	s_waitcnt lgkmcnt(6)
	v_mfma_f32_32x32x16_bf16 v[34:49], v[8:11], v[138:141], v[34:49]
	ds_read_b64_tr_b16 v[4:5], v246 offset:46080
	ds_read_b64_tr_b16 v[6:7], v246 offset:46592
	v_sub_f32_e32 v118, v124, v247
	v_exp_f32_e32 v136, v118
	v_sub_f32_e32 v118, v125, v247
	v_exp_f32_e32 v137, v118
	s_waitcnt lgkmcnt(6)
	v_mfma_f32_32x32x16_bf16 v[50:65], v[8:11], v[142:145], v[50:65]
	ds_read_b64_tr_b16 v[118:119], v246 offset:50176
	ds_read_b64_tr_b16 v[120:121], v246 offset:50688
	v_sub_f32_e32 v122, v126, v247
	v_exp_f32_e32 v138, v122
	v_sub_f32_e32 v122, v127, v247
	v_exp_f32_e32 v139, v122
	s_waitcnt lgkmcnt(6)
	v_mfma_f32_32x32x16_bf16 v[66:81], v[8:11], v[130:133], v[66:81]
	ds_read_b64_tr_b16 v[122:123], v246 offset:54272
	ds_read_b64_tr_b16 v[124:125], v246 offset:54784
	v_sub_f32_e32 v126, v128, v247
	v_exp_f32_e32 v140, v126
	v_sub_f32_e32 v126, v129, v247
	v_exp_f32_e32 v141, v126
	s_waitcnt lgkmcnt(6)
	v_mfma_f32_32x32x16_bf16 v[18:33], v[114:117], v[12:15], v[18:33]
	ds_read_b64_tr_b16 v[8:9], v246 offset:43008
	ds_read_b64_tr_b16 v[10:11], v246 offset:43520
	v_cvt_pk_bf16_f32 v126, v181, v203
	v_cvt_pk_bf16_f32 v127, v182, v183
	v_cvt_pk_bf16_f32 v128, v184, v185
	v_cvt_pk_bf16_f32 v129, v186, v187
	s_waitcnt lgkmcnt(6)
	v_mfma_f32_32x32x16_bf16 v[34:49], v[114:117], v[4:7], v[34:49]
	ds_read_b64_tr_b16 v[12:13], v246 offset:47104
	ds_read_b64_tr_b16 v[14:15], v246 offset:47616
	v_cvt_pk_bf16_f32 v130, v134, v135
	v_cvt_pk_bf16_f32 v131, v136, v137
	v_cvt_pk_bf16_f32 v132, v138, v139
	v_cvt_pk_bf16_f32 v133, v140, v141
	s_waitcnt lgkmcnt(6)
	v_mfma_f32_32x32x16_bf16 v[50:65], v[114:117], v[118:121], v[50:65]
	ds_read_b64_tr_b16 v[4:5], v246 offset:51200
	ds_read_b64_tr_b16 v[6:7], v246 offset:51712
	s_waitcnt lgkmcnt(6)
	v_mfma_f32_32x32x16_bf16 v[66:81], v[114:117], v[122:125], v[66:81]
	ds_read_b64_tr_b16 v[118:119], v246 offset:55296
	ds_read_b64_tr_b16 v[120:121], v246 offset:55808
	s_waitcnt lgkmcnt(6)
; __device__ __forceinline__ float max3f(float a,float b,float c){float r;asm("v_max3_f32 %0, %1, %2, %3":"=v"(r):"v"(a),"v"(b),"v"(c));return r;}
; __device__ __forceinline__ float max2f(float a,float b){float r;asm("v_max_f32_e32 %0, %1, %2":"=v"(r):"v"(a),"v"(b));return r;}
; #define A128_WAITBAR() asm volatile("s_waitcnt vmcnt(0) lgkmcnt(0)\n\ts_barrier":::"memory")
;   #define PINAB() asm volatile("":"+v"(ma),"+v"(mb))
;   #define ROT() do{ ks1=ks2; ks2=(ks2==2*KBUF)?0:ks2+KBUF; }while(0)
; template<int THRL,bool FIRST> __device__ __forceinline__ void step_main(f32x16&p0,f32x16&p1,f32x16&n0,f32x16&n1,St&S,lds_cptr kpn,lds_cptr qp,lds_cptr vp,float*wsf,int r32,int hi,float&rm){
;     ...
;   float ma,mb;
;     ...
;   PVG(8,pw2,vfa,12,0.f,0.f,0.f,0.f, do{ma=max3f(n0[0],n0[1],n1[0]);mb=max3f(n0[2],n0[3],n1[1]);PINAB();}while(0));
;   PVG(9,pw2,vfb,13,0.f,0.f,0.f,0.f, do{ma=max3f(ma,n1[2],n1[3]);mb=max3f(mb,n0[4],n0[5]);PINAB();}while(0));
;   PVG(10,pw2,vfc,14,0.f,0.f,0.f,0.f, do{ma=max3f(ma,n0[6],n0[7]);mb=max3f(mb,n1[4],n1[5]);PINAB();}while(0));
;   PVG(11,pw2,vfd,15,0.f,0.f,0.f,0.f, do{ma=max3f(ma,n1[6],n1[7]);mb=max3f(mb,n0[8],n0[9]);PINAB();}while(0));
;   PVG(12,pw3,vfa,16,0.f,0.f,0.f,0.f, do{ma=max3f(ma,n0[10],n0[11]);mb=max3f(mb,n1[8],n1[9]);PINAB();}while(0));
;   PVG(13,pw3,vfb,16,0.f,0.f,0.f,0.f, do{ma=max3f(ma,n1[10],n1[11]);mb=max3f(mb,n0[12],n0[13]);PINAB();}while(0));
;   PVG(14,pw3,vfc,16,0.f,0.f,0.f,0.f, do{ma=max3f(ma,n0[14],n0[15]);mb=max3f(mb,n1[12],n1[13]);PINAB();}while(0));
;   PVG(15,pw3,vfd,16,0.f,0.f,0.f,0.f, do{ma=max3f(ma,n1[14],n1[15]);ma=max2f(ma,mb);PINAB();}while(0));
;     ...
;   { auto rr=__builtin_amdgcn_permlane32_swap(__float_as_uint(ma),__float_as_uint(ma),false,false); rm=max2f(__uint_as_float(rr[0]),__uint_as_float(rr[1])); }
;     ...
;   S.l_reg+=sa;
; template<int THRL> __device__ __forceinline__ void unit(int qb,const bf16*Q,const bf16*K,const bf16*V,bf16*O,char*shm){
;     ...
;     DMA_K(2,ks2); DMA_V(1,VBUF);
;     step_main<THRL,true>(pA0,pA1,pB0,pB1,S,kp0+ks1,qp,vp0,wsf,r32,hi,rm); A128_WAITBAR(); ROT();
;     DMA_K(3,ks2); DMA_V(2,0);
;     step_main<THRL,false>(pB0,pB1,pA0,pA1,S,kp0+ks1,qp,vp0+VBUF,wsf,r32,hi,rm); A128_WAITBAR(); ROT();
;     for(t=2;t<NT-4;t+=2){
;       DMA_K(t+2,ks2); DMA_V(t+1,VBUF);
;       step_main<THRL,false>(pA0,pA1,pB0,pB1,S,kp0+ks1,qp,vp0,wsf,r32,hi,rm); A128_WAITBAR(); ROT();
	v_mfma_f32_32x32x16_bf16 v[18:33], v[126:129], v[8:11], v[18:33]
	ds_read_b64_tr_b16 v[114:115], v246 offset:44032
	ds_read_b64_tr_b16 v[116:117], v246 offset:44544
	v_max3_f32 v122, v98, v99, v82
	v_max3_f32 v123, v100, v101, v83
	s_nop 0
	s_waitcnt lgkmcnt(6)
	v_mfma_f32_32x32x16_bf16 v[34:49], v[126:129], v[12:15], v[34:49]
	ds_read_b64_tr_b16 v[8:9], v246 offset:48128
	ds_read_b64_tr_b16 v[10:11], v246 offset:48640
	v_max3_f32 v122, v122, v84, v85
	v_max3_f32 v123, v123, v102, v103
	s_nop 0
	s_waitcnt lgkmcnt(6)
	v_mfma_f32_32x32x16_bf16 v[50:65], v[126:129], v[4:7], v[50:65]
	ds_read_b64_tr_b16 v[12:13], v246 offset:52224
	ds_read_b64_tr_b16 v[14:15], v246 offset:52736
	v_max3_f32 v122, v122, v104, v105
	v_max3_f32 v123, v123, v86, v87
	s_nop 0
	s_waitcnt lgkmcnt(6)
	v_mfma_f32_32x32x16_bf16 v[66:81], v[126:129], v[118:121], v[66:81]
	ds_read_b64_tr_b16 v[4:5], v246 offset:56320
	ds_read_b64_tr_b16 v[6:7], v246 offset:56832
	v_max3_f32 v122, v122, v88, v89
	v_max3_f32 v123, v123, v106, v107
	s_nop 0
	s_waitcnt lgkmcnt(6)
	v_mfma_f32_32x32x16_bf16 v[18:33], v[130:133], v[114:117], v[18:33]
	v_max3_f32 v118, v122, v108, v109
	v_max3_f32 v119, v123, v90, v91
	s_nop 0
	s_waitcnt lgkmcnt(4)
	v_mfma_f32_32x32x16_bf16 v[34:49], v[130:133], v[8:11], v[34:49]
	v_max3_f32 v114, v118, v92, v93
	v_max3_f32 v115, v119, v110, v111
	s_nop 0
	s_waitcnt lgkmcnt(2)
	v_mfma_f32_32x32x16_bf16 v[50:65], v[130:133], v[12:15], v[50:65]
	v_max3_f32 v8, v114, v112, v113
	v_max3_f32 v9, v115, v94, v95
	s_nop 0
	s_waitcnt lgkmcnt(0)
	v_mfma_f32_32x32x16_bf16 v[66:81], v[130:133], v[4:7], v[66:81]
	v_max3_f32 v8, v8, v96, v97
	s_nop 0
	v_max_f32_e32 v8, v8, v9
	s_nop 0
	s_nop 0
	v_mov_b32_e32 v4, v8
	s_nop 1
	v_permlane32_swap_b32_e32 v8, v4
	v_max_f32_e32 v178, v8, v4
	v_add_f32_e32 v4, v17, v190
	v_add_f32_e32 v4, v191, v4
	v_add_f32_e32 v4, v192, v4
	v_add_f32_e32 v4, v193, v4
	v_add_f32_e32 v4, v194, v4
	v_add_f32_e32 v4, v195, v4
	v_add_f32_e32 v4, v196, v4
	v_add_f32_e32 v4, v197, v4
	v_add_f32_e32 v4, v198, v4
	v_add_f32_e32 v4, v199, v4
	v_add_f32_e32 v4, v200, v4
	v_add_f32_e32 v4, v201, v4
	v_add_f32_e32 v4, v202, v4
	v_add_f32_e32 v4, v179, v4
	v_add_f32_e32 v4, v180, v4
	v_add_f32_e32 v4, v181, v4
	v_add_f32_e32 v4, v203, v4
	v_add_f32_e32 v4, v182, v4
	v_add_f32_e32 v4, v183, v4
	v_add_f32_e32 v4, v184, v4
	v_add_f32_e32 v4, v185, v4
	v_add_f32_e32 v4, v186, v4
	v_add_f32_e32 v4, v187, v4
	v_add_f32_e32 v4, v134, v4
	v_add_f32_e32 v4, v135, v4
	v_add_f32_e32 v4, v136, v4
	v_add_f32_e32 v4, v137, v4
	v_add_f32_e32 v4, v138, v4
	v_add_f32_e32 v4, v139, v4
	v_add_f32_e32 v4, v140, v4
	s_waitcnt vmcnt(0) lgkmcnt(0)
	s_barrier
	v_add_f32_e32 v4, v141, v4
	v_add_f32_e32 v4, 0, v4
	s_add_i32 s87, s83, -4
	v_add_f32_e32 v251, v16, v4
	v_cmp_gt_u32_e64 s[6:7], 32, v243
	s_mov_b32 s88, 2
	v_lshl_add_u32 v16, v242, 2, s76
	s_movk_i32 s86, 0x2000
	s_mov_b32 s89, 0
	s_mov_b64 s[48:49], s[34:35]
	s_mov_b64 s[50:51], s[30:31]
	v_sub_f32_e32 v146, 0, v247
	v_sub_f32_e32 v147, 0, v247
	v_sub_f32_e32 v148, 0, v247
	v_sub_f32_e32 v149, 0, v247
	v_sub_f32_e32 v150, 0, v247
	v_sub_f32_e32 v151, 0, v247
	v_sub_f32_e32 v152, 0, v247
	v_sub_f32_e32 v153, 0, v247
	v_sub_f32_e32 v154, 0, v247
	v_sub_f32_e32 v155, 0, v247
	v_sub_f32_e32 v156, 0, v247
	v_sub_f32_e32 v157, 0, v247
	v_sub_f32_e32 v158, 0, v247
	v_sub_f32_e32 v159, 0, v247
	v_sub_f32_e32 v160, 0, v247
	v_sub_f32_e32 v161, 0, v247
	v_sub_f32_e32 v82, v82, v247
	v_sub_f32_e32 v83, v83, v247
	v_sub_f32_e32 v84, v84, v247
	v_sub_f32_e32 v85, v85, v247
	v_sub_f32_e32 v86, v86, v247
	v_sub_f32_e32 v87, v87, v247
	v_sub_f32_e32 v88, v88, v247
	v_sub_f32_e32 v89, v89, v247
	v_sub_f32_e32 v90, v90, v247
	v_sub_f32_e32 v91, v91, v247
	v_sub_f32_e32 v92, v92, v247
	v_sub_f32_e32 v93, v93, v247
	v_sub_f32_e32 v94, v94, v247
	v_sub_f32_e32 v95, v95, v247
	v_sub_f32_e32 v96, v96, v247
	v_sub_f32_e32 v97, v97, v247
	v_sub_f32_e32 v98, v98, v247
	v_sub_f32_e32 v99, v99, v247
	v_sub_f32_e32 v100, v100, v247
	v_sub_f32_e32 v101, v101, v247
	v_sub_f32_e32 v102, v102, v247
	v_sub_f32_e32 v103, v103, v247
	v_sub_f32_e32 v104, v104, v247
	v_sub_f32_e32 v105, v105, v247
	v_sub_f32_e32 v106, v106, v247
	v_sub_f32_e32 v107, v107, v247
	v_sub_f32_e32 v108, v108, v247
	v_sub_f32_e32 v109, v109, v247
	v_sub_f32_e32 v110, v110, v247
	v_sub_f32_e32 v111, v111, v247
	v_sub_f32_e32 v112, v112, v247
	v_sub_f32_e32 v113, v113, v247
	v_sub_f32_e32 v178, v178, v247
	s_add_u32 s58, s50, 0xfff40000
	s_addc_u32 s59, s51, -1
	s_add_i32 s4, s86, s80
	s_mov_b32 s5, m0
	s_mov_b32 m0, s4
	s_nop 0
	global_load_lds_dwordx4 v252, s[58:59]
	s_add_i32 s4, s80, 0x4000
	s_mov_b32 m0, s4
	s_nop 0
	global_load_lds_dwordx4 v252, s[50:51]
	s_mov_b32 m0, s5
	ds_read_b128 v[164:167], v248
	ds_read_b128 v[168:171], v248 offset:1024
	ds_read_b128 v[172:175], v248 offset:2048
	ds_read_b128 v[236:239], v248 offset:3072
	v_add_u32_e32 v240, s89, v249
	ds_read_b128 v[204:207], v240
	ds_read_b128 v[208:211], v240 offset:512
	ds_read_b128 v[212:215], v240 offset:2048
	ds_read_b128 v[216:219], v240 offset:2560
	ds_read_b128 v[220:223], v240 offset:4096
	ds_read_b128 v[224:227], v240 offset:4608
	ds_read_b128 v[228:231], v240 offset:6144
	ds_read_b128 v[232:235], v240 offset:6656
	s_waitcnt vmcnt(0) lgkmcnt(0)
	s_barrier
	s_branch .LBB0_436

; #define SB() __builtin_amdgcn_sched_barrier(0)
; #define MF32(a,b,c) __builtin_amdgcn_mfma_f32_32x32x16_bf16(a,b,c,0,0,0)
; #define EXP1(x) x=__builtin_amdgcn_exp2f((x)-mh_)
; __device__ __forceinline__ bf16x8 vfrag(lds_cptr vp,int i){ const s16x4 lo=vtr(vp+(i&3)*4096+(i>>2)*1024), hh=vtr(vp+(i&3)*4096+(i>>2)*1024+512); return (bf16x8){lo[0],lo[1],lo[2],lo[3],hh[0],hh[1],hh[2],hh[3]}; }
; __device__ __forceinline__ u32x4 packw(const f32x16&p,int base){ u32x4 w; w[0]=cvtpk_s(p[base],p[base+1]); w[1]=cvtpk_s(p[base+2],p[base+3]); w[2]=cvtpk_s(p[base+4],p[base+5]); w[3]=cvtpk_s(p[base+6],p[base+7]); return w; }
; template<int THRL,bool FIRST> __device__ __forceinline__ void step_main(f32x16&p0,f32x16&p1,f32x16&n0,f32x16&n1,St&S,lds_cptr kpn,lds_cptr qp,lds_cptr vp,float*wsf,int r32,int hi,float&rm){
;     ...
;   bf16x8 ka=KF(0),kb=KF(1),kc=KF(2),kd=KF(3),qa=QF(0),qb=QF(1);
;   decide<THRL,FIRST>(rm,S,wsf,r32,hi);
;   u32x4 pw0,pw1,pw2,pw3; const float mh_=S.mhat; const f32x16 z=f32x16{};
;   SB();
;   n0=MF32(ka,qa,z); ka=KF(4); EXP1(p0[0]);EXP1(p0[1]);EXP1(p0[2]); SB();
;   n1=MF32(kb,qa,z); kb=KF(5); qa=QF(2); EXP1(p0[3]);EXP1(p0[4]);EXP1(p0[5]); SB();
;   n0=MF32(kc,qb,n0);   kc=KF(6); EXP1(p0[6]);EXP1(p0[7]);EXP1(p0[8]); SB();
;   n1=MF32(kd,qb,n1);   kd=KF(7); qb=QF(3); EXP1(p0[9]);EXP1(p0[10]);EXP1(p0[11]); SB();
;   bf16x8 vfa=vfrag(vp,0);
;   n0=MF32(ka,qa,n0);   EXP1(p0[12]);EXP1(p0[13]);EXP1(p0[14]); pw0=packw(p0,0); SB();
;   bf16x8 vfb=vfrag(vp,1);
;   n1=MF32(kb,qa,n1);   EXP1(p0[15]);EXP1(p1[0]);EXP1(p1[1]); SB();
;   bf16x8 vfc=vfrag(vp,2);
;   n0=MF32(kc,qb,n0);   EXP1(p1[2]);EXP1(p1[3]);EXP1(p1[4]); pw1=packw(p0,8); SB();
;   bf16x8 vfd=vfrag(vp,3);
;   n1=MF32(kd,qb,n1);   EXP1(p1[5]);EXP1(p1[6]);EXP1(p1[7]); SB();
;     ...
;   float sa=p0[0]+p0[1];
;     ...
;   PVG(0,pw0,vfa,4, p0[2],p0[3],p0[4],p0[5],   do{EXP1(p1[8]);EXP1(p1[9]);}while(0));
;   PVG(1,pw0,vfb,5, p0[6],p0[7],p0[8],p0[9], do{EXP1(p1[10]);EXP1(p1[11]);}while(0));
;   PVG(2,pw0,vfc,6, p0[10],p0[11],p0[12],p0[13], do{EXP1(p1[12]);EXP1(p1[13]);}while(0));
;   PVG(3,pw0,vfd,7, p0[14],p0[15],p1[0],p1[1],   do{EXP1(p1[14]);EXP1(p1[15]);}while(0));
;   PVG(4,pw1,vfa,8, p1[2],p1[3],p1[4],p1[5],   pw2=packw(p1,0));
;   PVG(5,pw1,vfb,9, p1[6],p1[7],p1[8],p1[9], pw3=packw(p1,8));
;   PVG(6,pw1,vfc,10, p1[10],p1[11],p1[12],p1[13], do{}while(0));
;   PVG(7,pw1,vfd,11, p1[14],p1[15],0.f,0.f, do{}while(0));
.LBB0_435:
	s_add_i32 s88, s88, 2
	v_mfma_f32_32x32x16_bf16 v[98:113], v[204:207], v[164:167], v[146:161]
	v_exp_f32_e32 v130, v130
	v_exp_f32_e32 v131, v131
	v_exp_f32_e32 v132, v132
	v_exp_f32_e32 v133, v133
	v_exp_f32_e32 v134, v134
	v_exp_f32_e32 v135, v135
	v_mfma_f32_32x32x16_bf16 v[82:97], v[208:211], v[164:167], v[146:161]
	s_add_u32 s58, s48, 0xc0000
	s_addc_u32 s59, s49, 0
	s_mov_b32 s4, m0
	s_mov_b32 m0, s78
	s_nop 0
	global_load_lds_dwordx4 v250, s[58:59]
	s_mov_b32 m0, s4
	v_mfma_f32_32x32x16_bf16 v[98:113], v[212:215], v[168:171], v[98:113]
	s_add_u32 s58, s48, 0xc0080
	s_addc_u32 s59, s49, 0
	s_mov_b32 s4, m0
	s_mov_b32 m0, s79
	s_nop 0
	global_load_lds_dwordx4 v250, s[58:59]
	s_mov_b32 m0, s4
	v_exp_f32_e32 v136, v136
	v_exp_f32_e32 v137, v137
	v_exp_f32_e32 v138, v138
	v_mfma_f32_32x32x16_bf16 v[82:97], v[216:219], v[168:171], v[82:97]
	v_exp_f32_e32 v139, v139
	v_exp_f32_e32 v140, v140
	v_exp_f32_e32 v141, v141
	v_mfma_f32_32x32x16_bf16 v[98:113], v[220:223], v[172:175], v[98:113]
	v_exp_f32_e32 v142, v142
	ds_read_b64_tr_b16 v[4:5], v246 offset:40960
	ds_read_b64_tr_b16 v[6:7], v246 offset:41472
	v_exp_f32_e32 v143, v143
	v_exp_f32_e32 v144, v144
	v_cvt_pk_bf16_f32 v8, v130, v131
	v_cvt_pk_bf16_f32 v9, v132, v133
	v_cvt_pk_bf16_f32 v10, v134, v135
	v_cvt_pk_bf16_f32 v11, v136, v137
	v_mfma_f32_32x32x16_bf16 v[82:97], v[224:227], v[172:175], v[82:97]
	ds_read_b64_tr_b16 v[178:179], v246 offset:45056
	ds_read_b64_tr_b16 v[180:181], v246 offset:45568
	v_exp_f32_e32 v145, v145
	v_exp_f32_e32 v114, v114
	v_exp_f32_e32 v115, v115
	v_mfma_f32_32x32x16_bf16 v[98:113], v[228:231], v[236:239], v[98:113]
	ds_read_b64_tr_b16 v[182:183], v246 offset:49152
	ds_read_b64_tr_b16 v[184:185], v246 offset:49664
	v_exp_f32_e32 v116, v116
	v_exp_f32_e32 v117, v117
	v_exp_f32_e32 v118, v118
	v_cvt_pk_bf16_f32 v186, v138, v139
	v_cvt_pk_bf16_f32 v187, v140, v141
	v_cvt_pk_bf16_f32 v188, v142, v143
	v_cvt_pk_bf16_f32 v189, v144, v145
	v_mfma_f32_32x32x16_bf16 v[82:97], v[232:235], v[236:239], v[82:97]
	v_add_u32_e32 v240, s89, v249
	ds_read_b64_tr_b16 v[190:191], v246 offset:53248
	ds_read_b64_tr_b16 v[192:193], v246 offset:53760
	v_exp_f32_e32 v119, v119
	v_exp_f32_e32 v120, v120
	v_exp_f32_e32 v121, v121
	s_waitcnt lgkmcnt(6)
	v_mfma_f32_32x32x16_bf16 v[18:33], v[8:11], v[4:7], v[18:33]
	ds_read_b64_tr_b16 v[12:13], v246 offset:41984
	ds_read_b64_tr_b16 v[14:15], v246 offset:42496
	ds_read_b128 v[204:207], v240
	v_add_f32_e32 v194, v130, v131
	v_exp_f32_e32 v122, v122
	v_exp_f32_e32 v123, v123
	v_add_f32_e32 v194, v132, v194
	v_add_f32_e32 v4, v133, v194
	v_add_f32_e32 v4, v134, v4
	v_add_f32_e32 v194, v135, v4
	s_waitcnt lgkmcnt(7)
	v_mfma_f32_32x32x16_bf16 v[34:49], v[8:11], v[178:181], v[34:49]
	ds_read_b64_tr_b16 v[4:5], v246 offset:46080
	ds_read_b64_tr_b16 v[6:7], v246 offset:46592
	ds_read_b128 v[208:211], v240 offset:512
	v_exp_f32_e32 v124, v124
	v_exp_f32_e32 v125, v125
	v_add_f32_e32 v194, v136, v194
	v_add_f32_e32 v178, v137, v194
	v_add_f32_e32 v178, v138, v178
	v_add_f32_e32 v194, v139, v178
	s_waitcnt lgkmcnt(8)
	v_mfma_f32_32x32x16_bf16 v[50:65], v[8:11], v[182:185], v[50:65]
	ds_read_b64_tr_b16 v[178:179], v246 offset:50176
	ds_read_b64_tr_b16 v[180:181], v246 offset:50688
	ds_read_b128 v[212:215], v240 offset:2048
	v_exp_f32_e32 v126, v126
	v_exp_f32_e32 v127, v127
	v_add_f32_e32 v194, v140, v194
	v_add_f32_e32 v182, v141, v194
	v_add_f32_e32 v182, v142, v182
	v_add_f32_e32 v194, v143, v182
	s_waitcnt lgkmcnt(9)
	v_mfma_f32_32x32x16_bf16 v[66:81], v[8:11], v[190:193], v[66:81]
	ds_read_b64_tr_b16 v[182:183], v246 offset:54272
	ds_read_b64_tr_b16 v[184:185], v246 offset:54784
	ds_read_b128 v[216:219], v240 offset:2560
	v_exp_f32_e32 v128, v128
	v_exp_f32_e32 v129, v129
	v_add_f32_e32 v194, v144, v194
	v_add_f32_e32 v8, v145, v194
	v_add_f32_e32 v8, v114, v8
	v_add_f32_e32 v190, v115, v8
	s_waitcnt lgkmcnt(10)
	v_mfma_f32_32x32x16_bf16 v[18:33], v[186:189], v[12:15], v[18:33]
	ds_read_b64_tr_b16 v[8:9], v246 offset:43008
	ds_read_b64_tr_b16 v[10:11], v246 offset:43520
	ds_read_b128 v[220:223], v240 offset:4096
	v_add_f32_e32 v190, v116, v190
	v_add_f32_e32 v190, v117, v190
	v_add_f32_e32 v190, v118, v190
	v_add_f32_e32 v194, v119, v190
	v_cvt_pk_bf16_f32 v12, v114, v115
	v_cvt_pk_bf16_f32 v13, v116, v117
	v_cvt_pk_bf16_f32 v14, v118, v119
	v_cvt_pk_bf16_f32 v15, v120, v121
	s_waitcnt lgkmcnt(10)
	v_mfma_f32_32x32x16_bf16 v[34:49], v[186:189], v[4:7], v[34:49]
	ds_read_b64_tr_b16 v[190:191], v246 offset:47104
	ds_read_b64_tr_b16 v[192:193], v246 offset:47616
	ds_read_b128 v[224:227], v240 offset:4608
	v_add_f32_e32 v194, v120, v194
	v_add_f32_e32 v194, v121, v194
	v_add_f32_e32 v194, v122, v194
	v_add_f32_e32 v198, v123, v194
	v_cvt_pk_bf16_f32 v4, v122, v123
	v_cvt_pk_bf16_f32 v5, v124, v125
	v_cvt_pk_bf16_f32 v6, v126, v127
	v_cvt_pk_bf16_f32 v7, v128, v129
	s_waitcnt lgkmcnt(10)
	v_mfma_f32_32x32x16_bf16 v[50:65], v[186:189], v[178:181], v[50:65]
	ds_read_b64_tr_b16 v[194:195], v246 offset:51200
	ds_read_b64_tr_b16 v[196:197], v246 offset:51712
	ds_read_b128 v[228:231], v240 offset:6144
	v_add_f32_e32 v198, v124, v198
	v_add_f32_e32 v198, v125, v198
	v_add_f32_e32 v198, v126, v198
	v_add_f32_e32 v198, v127, v198
	s_waitcnt lgkmcnt(10)
	v_mfma_f32_32x32x16_bf16 v[66:81], v[186:189], v[182:185], v[66:81]
	ds_read_b64_tr_b16 v[178:179], v246 offset:55296
	ds_read_b64_tr_b16 v[180:181], v246 offset:55808
	ds_read_b128 v[232:235], v240 offset:6656
	v_add_f32_e32 v198, v128, v198
	v_add_f32_e32 v198, v129, v198
	v_add_f32_e32 v198, 0, v198
	s_waitcnt lgkmcnt(10)
	v_mfma_f32_32x32x16_bf16 v[18:33], v[12:15], v[8:11], v[18:33]
	ds_read_b64_tr_b16 v[182:183], v246 offset:44032
	ds_read_b64_tr_b16 v[184:185], v246 offset:44544
	s_cmpk_lt_u32 s84, 0x100
	s_cbranch_scc0 .Lattn_kdma_7
	s_add_i32 s4, s86, s80
	s_add_u32 s58, s50, 0x180000
	s_addc_u32 s59, s51, 0
	s_mov_b32 s5, m0
	s_mov_b32 m0, s4
	s_nop 0
	global_load_lds_dwordx4 v252, s[58:59]
	s_mov_b32 m0, s5
; __device__ __forceinline__ float max3f(float a,float b,float c){float r;asm("v_max3_f32 %0, %1, %2, %3":"=v"(r):"v"(a),"v"(b),"v"(c));return r;}
; __device__ __forceinline__ float max2f(float a,float b){float r;asm("v_max_f32_e32 %0, %1, %2":"=v"(r):"v"(a),"v"(b));return r;}
; #define EXP1(x) x=__builtin_amdgcn_exp2f((x)-mh_)
;   #define PINAB() asm volatile("":"+v"(ma),"+v"(mb))
; template<int THRL,bool FIRST> __device__ __forceinline__ void step_main(f32x16&p0,f32x16&p1,f32x16&n0,f32x16&n1,St&S,lds_cptr kpn,lds_cptr qp,lds_cptr vp,float*wsf,int r32,int hi,float&rm){
;     ...
;   PVG(0,pw0,vfa,4, p0[2],p0[3],p0[4],p0[5],   do{EXP1(p1[8]);EXP1(p1[9]);}while(0));
;   PVG(1,pw0,vfb,5, p0[6],p0[7],p0[8],p0[9], do{EXP1(p1[10]);EXP1(p1[11]);}while(0));
;   PVG(2,pw0,vfc,6, p0[10],p0[11],p0[12],p0[13], do{EXP1(p1[12]);EXP1(p1[13]);}while(0));
;   PVG(3,pw0,vfd,7, p0[14],p0[15],p1[0],p1[1],   do{EXP1(p1[14]);EXP1(p1[15]);}while(0));
;   PVG(4,pw1,vfa,8, p1[2],p1[3],p1[4],p1[5],   pw2=packw(p1,0));
;   PVG(5,pw1,vfb,9, p1[6],p1[7],p1[8],p1[9], pw3=packw(p1,8));
;   PVG(6,pw1,vfc,10, p1[10],p1[11],p1[12],p1[13], do{}while(0));
;   PVG(7,pw1,vfd,11, p1[14],p1[15],0.f,0.f, do{}while(0));
;   float ma,mb;
;     ...
;   PVG(8,pw2,vfa,12,0.f,0.f,0.f,0.f, do{ma=max3f(n0[0],n0[1],n1[0]);mb=max3f(n0[2],n0[3],n1[1]);PINAB();}while(0));
;   PVG(9,pw2,vfb,13,0.f,0.f,0.f,0.f, do{ma=max3f(ma,n1[2],n1[3]);mb=max3f(mb,n0[4],n0[5]);PINAB();}while(0));
;   PVG(10,pw2,vfc,14,0.f,0.f,0.f,0.f, do{ma=max3f(ma,n0[6],n0[7]);mb=max3f(mb,n1[4],n1[5]);PINAB();}while(0));
;   PVG(11,pw2,vfd,15,0.f,0.f,0.f,0.f, do{ma=max3f(ma,n1[6],n1[7]);mb=max3f(mb,n0[8],n0[9]);PINAB();}while(0));
;   PVG(12,pw3,vfa,16,0.f,0.f,0.f,0.f, do{ma=max3f(ma,n0[10],n0[11]);mb=max3f(mb,n1[8],n1[9]);PINAB();}while(0));
;   PVG(13,pw3,vfb,16,0.f,0.f,0.f,0.f, do{ma=max3f(ma,n1[10],n1[11]);mb=max3f(mb,n0[12],n0[13]);PINAB();}while(0));
;   PVG(14,pw3,vfc,16,0.f,0.f,0.f,0.f, do{ma=max3f(ma,n0[14],n0[15]);mb=max3f(mb,n1[12],n1[13]);PINAB();}while(0));
;   PVG(15,pw3,vfd,16,0.f,0.f,0.f,0.f, do{ma=max3f(ma,n1[14],n1[15]);ma=max2f(ma,mb);PINAB();}while(0));
;     ...
;   { auto rr=__builtin_amdgcn_permlane32_swap(__float_as_uint(ma),__float_as_uint(ma),false,false); rm=max2f(__uint_as_float(rr[0]),__uint_as_float(rr[1])); }
;     ...
;   S.l_reg+=sa;
.Lattn_kdma_7:
	v_max3_f32 v186, v98, v99, v82
	v_max3_f32 v187, v100, v101, v83
	s_nop 0
	s_waitcnt lgkmcnt(9)
	v_mfma_f32_32x32x16_bf16 v[34:49], v[12:15], v[190:193], v[34:49]
	ds_read_b64_tr_b16 v[8:9], v246 offset:48128
	ds_read_b64_tr_b16 v[10:11], v246 offset:48640
	v_max3_f32 v199, v186, v84, v85
	v_max3_f32 v200, v187, v102, v103
	s_nop 0
	s_waitcnt lgkmcnt(8)
	v_mfma_f32_32x32x16_bf16 v[50:65], v[12:15], v[194:197], v[50:65]
	ds_read_b64_tr_b16 v[186:187], v246 offset:52224
	ds_read_b64_tr_b16 v[188:189], v246 offset:52736
	v_max3_f32 v199, v199, v104, v105
	v_max3_f32 v200, v200, v86, v87
	s_nop 0
	s_waitcnt lgkmcnt(7)
	v_mfma_f32_32x32x16_bf16 v[66:81], v[12:15], v[178:181], v[66:81]
	ds_read_b64_tr_b16 v[190:191], v246 offset:56320
	ds_read_b64_tr_b16 v[192:193], v246 offset:56832
	v_max3_f32 v194, v199, v88, v89
	v_max3_f32 v195, v200, v106, v107
	s_nop 0
	s_waitcnt lgkmcnt(6)
	v_mfma_f32_32x32x16_bf16 v[18:33], v[4:7], v[182:185], v[18:33]
	s_cmpk_lt_u32 s84, 0x100
	s_cbranch_scc1 .Lattn_kdma_8
	s_add_i32 s4, s86, s80
	s_add_u32 s58, s50, 0x180000
	s_addc_u32 s59, s51, 0
	s_mov_b32 s5, m0
	s_mov_b32 m0, s4
	s_nop 0
	global_load_lds_dwordx4 v252, s[58:59]
	s_mov_b32 m0, s5
.Lattn_kdma_8:
	s_add_i32 s4, s89, 0x2000
	s_cmpk_lg_i32 s89, 0x4000
	s_cselect_b32 s86, s4, 0
	v_max3_f32 v12, v194, v108, v109
	v_max3_f32 v13, v195, v90, v91
	s_nop 0
	s_waitcnt lgkmcnt(4)
	v_mfma_f32_32x32x16_bf16 v[34:49], v[4:7], v[8:11], v[34:49]
	v_max3_f32 v12, v12, v92, v93
	v_max3_f32 v13, v13, v110, v111
	s_nop 0
	s_waitcnt lgkmcnt(2)
	v_mfma_f32_32x32x16_bf16 v[50:65], v[4:7], v[186:189], v[50:65]
	v_max3_f32 v8, v12, v112, v113
	v_max3_f32 v9, v13, v94, v95
	s_nop 0
	s_waitcnt lgkmcnt(0)
	v_mfma_f32_32x32x16_bf16 v[66:81], v[4:7], v[190:193], v[66:81]
	v_max3_f32 v8, v8, v96, v97
	s_nop 0
	v_max_f32_e32 v8, v8, v9
	s_nop 0
	s_add_u32 s50, s50, 0x180000
	s_addc_u32 s51, s51, 0
	s_add_u32 s48, s48, 0x180000
	s_waitcnt vmcnt(1) lgkmcnt(0)
	s_barrier
	s_addc_u32 s49, s49, 0
	v_mov_b32_e32 v4, v8
	v_add_f32_e32 v251, v17, v198
	s_cmp_lt_u32 s88, s87
	v_permlane32_swap_b32_e32 v8, v4
	v_max_f32_e32 v178, v8, v4
	s_cbranch_scc0 .LBB0_443

; #define SB() __builtin_amdgcn_sched_barrier(0)
; #define MF32(a,b,c) __builtin_amdgcn_mfma_f32_32x32x16_bf16(a,b,c,0,0,0)
; #define EXP1(x) x=__builtin_amdgcn_exp2f((x)-mh_)
; __device__ __forceinline__ bf16x8 vfrag(lds_cptr vp,int i){ const s16x4 lo=vtr(vp+(i&3)*4096+(i>>2)*1024), hh=vtr(vp+(i&3)*4096+(i>>2)*1024+512); return (bf16x8){lo[0],lo[1],lo[2],lo[3],hh[0],hh[1],hh[2],hh[3]}; }
; __device__ __forceinline__ u32x4 packw(const f32x16&p,int base){ u32x4 w; w[0]=cvtpk_s(p[base],p[base+1]); w[1]=cvtpk_s(p[base+2],p[base+3]); w[2]=cvtpk_s(p[base+4],p[base+5]); w[3]=cvtpk_s(p[base+6],p[base+7]); return w; }
; template<int THRL,bool FIRST> __device__ __forceinline__ void step_main(f32x16&p0,f32x16&p1,f32x16&n0,f32x16&n1,St&S,lds_cptr kpn,lds_cptr qp,lds_cptr vp,float*wsf,int r32,int hi,float&rm){
;     ...
;   bf16x8 ka=KF(0),kb=KF(1),kc=KF(2),kd=KF(3),qa=QF(0),qb=QF(1);
;   decide<THRL,FIRST>(rm,S,wsf,r32,hi);
;   u32x4 pw0,pw1,pw2,pw3; const float mh_=S.mhat; const f32x16 z=f32x16{};
;   SB();
;   n0=MF32(ka,qa,z); ka=KF(4); EXP1(p0[0]);EXP1(p0[1]);EXP1(p0[2]); SB();
;   n1=MF32(kb,qa,z); kb=KF(5); qa=QF(2); EXP1(p0[3]);EXP1(p0[4]);EXP1(p0[5]); SB();
;   n0=MF32(kc,qb,n0);   kc=KF(6); EXP1(p0[6]);EXP1(p0[7]);EXP1(p0[8]); SB();
;   n1=MF32(kd,qb,n1);   kd=KF(7); qb=QF(3); EXP1(p0[9]);EXP1(p0[10]);EXP1(p0[11]); SB();
;   bf16x8 vfa=vfrag(vp,0);
;   n0=MF32(ka,qa,n0);   EXP1(p0[12]);EXP1(p0[13]);EXP1(p0[14]); pw0=packw(p0,0); SB();
;   bf16x8 vfb=vfrag(vp,1);
;   n1=MF32(kb,qa,n1);   EXP1(p0[15]);EXP1(p1[0]);EXP1(p1[1]); SB();
;   bf16x8 vfc=vfrag(vp,2);
;   n0=MF32(kc,qb,n0);   EXP1(p1[2]);EXP1(p1[3]);EXP1(p1[4]); pw1=packw(p0,8); SB();
;   bf16x8 vfd=vfrag(vp,3);
;   n1=MF32(kd,qb,n1);   EXP1(p1[5]);EXP1(p1[6]);EXP1(p1[7]); SB();
;     ...
;   float sa=p0[0]+p0[1];
;     ...
;   PVG(0,pw0,vfa,4, p0[2],p0[3],p0[4],p0[5],   do{EXP1(p1[8]);EXP1(p1[9]);}while(0));
;   PVG(1,pw0,vfb,5, p0[6],p0[7],p0[8],p0[9], do{EXP1(p1[10]);EXP1(p1[11]);}while(0));
;   PVG(2,pw0,vfc,6, p0[10],p0[11],p0[12],p0[13], do{EXP1(p1[12]);EXP1(p1[13]);}while(0));
;   PVG(3,pw0,vfd,7, p0[14],p0[15],p1[0],p1[1],   do{EXP1(p1[14]);EXP1(p1[15]);}while(0));
;   PVG(4,pw1,vfa,8, p1[2],p1[3],p1[4],p1[5],   pw2=packw(p1,0));
;   PVG(5,pw1,vfb,9, p1[6],p1[7],p1[8],p1[9], pw3=packw(p1,8));
;   PVG(6,pw1,vfc,10, p1[10],p1[11],p1[12],p1[13], do{}while(0));
;   PVG(7,pw1,vfd,11, p1[14],p1[15],0.f,0.f, do{}while(0));
.LBB0_440:
	v_mfma_f32_32x32x16_bf16 v[130:145], v[204:207], v[164:167], v[146:161]
	v_exp_f32_e32 v190, v98
	v_exp_f32_e32 v191, v99
	v_exp_f32_e32 v192, v100
	v_mfma_f32_32x32x16_bf16 v[114:129], v[208:211], v[164:167], v[146:161]
	s_mov_b32 s4, m0
	s_mov_b32 m0, s77
	s_nop 0
	global_load_lds_dwordx4 v250, s[48:49]
	s_mov_b32 m0, s4
	v_exp_f32_e32 v193, v101
	v_exp_f32_e32 v194, v102
	v_exp_f32_e32 v195, v103
	v_mfma_f32_32x32x16_bf16 v[130:145], v[212:215], v[168:171], v[130:145]
	s_add_u32 s58, s48, 0x80
	s_addc_u32 s59, s49, 0
	s_mov_b32 s4, m0
	s_mov_b32 m0, s39
	s_nop 0
	global_load_lds_dwordx4 v250, s[58:59]
	s_mov_b32 m0, s4
	v_exp_f32_e32 v196, v104
	v_exp_f32_e32 v197, v105
	v_exp_f32_e32 v198, v106
	v_mfma_f32_32x32x16_bf16 v[114:129], v[216:219], v[168:171], v[114:129]
	v_exp_f32_e32 v17, v107
	v_exp_f32_e32 v199, v108
	v_exp_f32_e32 v200, v109
	v_mfma_f32_32x32x16_bf16 v[130:145], v[220:223], v[172:175], v[130:145]
	v_exp_f32_e32 v201, v110
	ds_read_b64_tr_b16 v[4:5], v246 offset:24576
	ds_read_b64_tr_b16 v[6:7], v246 offset:25088
	v_exp_f32_e32 v202, v111
	v_exp_f32_e32 v178, v112
	v_cvt_pk_bf16_f32 v8, v190, v191
	v_cvt_pk_bf16_f32 v9, v192, v193
	v_cvt_pk_bf16_f32 v10, v194, v195
	v_cvt_pk_bf16_f32 v11, v196, v197
	v_mfma_f32_32x32x16_bf16 v[114:129], v[224:227], v[172:175], v[114:129]
	ds_read_b64_tr_b16 v[106:107], v246 offset:28672
	ds_read_b64_tr_b16 v[108:109], v246 offset:29184
	v_exp_f32_e32 v180, v82
	v_exp_f32_e32 v179, v113
	v_exp_f32_e32 v181, v83
	v_mfma_f32_32x32x16_bf16 v[130:145], v[228:231], v[236:239], v[130:145]
	ds_read_b64_tr_b16 v[110:111], v246 offset:32768
	ds_read_b64_tr_b16 v[112:113], v246 offset:33280
	v_exp_f32_e32 v182, v84
	v_exp_f32_e32 v183, v85
	v_exp_f32_e32 v184, v86
	v_cvt_pk_bf16_f32 v82, v198, v17
	v_cvt_pk_bf16_f32 v83, v199, v200
	v_cvt_pk_bf16_f32 v84, v201, v202
	v_cvt_pk_bf16_f32 v85, v178, v179
	v_mfma_f32_32x32x16_bf16 v[114:129], v[232:235], v[236:239], v[114:129]
	v_add_u32_e32 v240, s86, v249
	ds_read_b64_tr_b16 v[98:99], v246 offset:36864
	ds_read_b64_tr_b16 v[100:101], v246 offset:37376
	v_exp_f32_e32 v185, v87
	v_exp_f32_e32 v186, v88
	v_exp_f32_e32 v187, v89
	s_waitcnt lgkmcnt(6)
	v_mfma_f32_32x32x16_bf16 v[18:33], v[8:11], v[4:7], v[18:33]
	ds_read_b128 v[204:207], v240
	v_add_f32_e32 v86, v190, v191
	ds_read_b64_tr_b16 v[12:13], v246 offset:25600
	ds_read_b64_tr_b16 v[14:15], v246 offset:26112
	v_add_f32_e32 v86, v192, v86
	v_exp_f32_e32 v103, v91
	v_add_f32_e32 v4, v193, v86
	v_add_f32_e32 v4, v194, v4
	v_add_f32_e32 v86, v195, v4
	v_exp_f32_e32 v102, v90
	s_waitcnt lgkmcnt(7)
	v_mfma_f32_32x32x16_bf16 v[34:49], v[8:11], v[106:109], v[34:49]
	ds_read_b64_tr_b16 v[4:5], v246 offset:29696
	ds_read_b64_tr_b16 v[6:7], v246 offset:30208
	ds_read_b128 v[208:211], v240 offset:512
	v_add_f32_e32 v86, v196, v86
	v_add_f32_e32 v86, v197, v86
	v_add_f32_e32 v86, v198, v86
	v_exp_f32_e32 v104, v92
	v_add_f32_e32 v17, v17, v86
	v_exp_f32_e32 v105, v93
	s_waitcnt lgkmcnt(8)
	v_mfma_f32_32x32x16_bf16 v[50:65], v[8:11], v[110:113], v[50:65]
	ds_read_b64_tr_b16 v[86:87], v246 offset:33792
	ds_read_b64_tr_b16 v[88:89], v246 offset:34304
	ds_read_b128 v[212:215], v240 offset:2048
	v_add_f32_e32 v17, v199, v17
	v_add_f32_e32 v17, v200, v17
	v_add_f32_e32 v17, v201, v17
	v_exp_f32_e32 v106, v94
	v_add_f32_e32 v17, v202, v17
	v_exp_f32_e32 v107, v95
	s_waitcnt lgkmcnt(9)
	v_mfma_f32_32x32x16_bf16 v[66:81], v[8:11], v[98:101], v[66:81]
	ds_read_b64_tr_b16 v[90:91], v246 offset:37888
	ds_read_b64_tr_b16 v[92:93], v246 offset:38400
	ds_read_b128 v[216:219], v240 offset:2560
	v_add_f32_e32 v17, v178, v17
	v_add_f32_e32 v8, v179, v17
	v_add_f32_e32 v8, v180, v8
	v_exp_f32_e32 v108, v96
	v_add_f32_e32 v17, v181, v8
	v_exp_f32_e32 v109, v97
	s_waitcnt lgkmcnt(9)
	v_mfma_f32_32x32x16_bf16 v[18:33], v[82:85], v[12:15], v[18:33]
	ds_read_b64_tr_b16 v[8:9], v246 offset:26624
	ds_read_b64_tr_b16 v[10:11], v246 offset:27136
	ds_read_b128 v[220:223], v240 offset:4096
	v_add_f32_e32 v17, v182, v17
	v_add_f32_e32 v17, v183, v17
	v_add_f32_e32 v17, v184, v17
	v_add_f32_e32 v17, v185, v17
	v_cvt_pk_bf16_f32 v12, v180, v181
	v_cvt_pk_bf16_f32 v13, v182, v183
	v_cvt_pk_bf16_f32 v14, v184, v185
	v_cvt_pk_bf16_f32 v15, v186, v187
	s_waitcnt lgkmcnt(10)
	v_mfma_f32_32x32x16_bf16 v[34:49], v[82:85], v[4:7], v[34:49]
	ds_read_b64_tr_b16 v[94:95], v246 offset:30720
	ds_read_b64_tr_b16 v[96:97], v246 offset:31232
	ds_read_b128 v[224:227], v240 offset:4608
	v_add_f32_e32 v17, v186, v17
	v_add_f32_e32 v17, v187, v17
	v_add_f32_e32 v17, v102, v17
	v_add_f32_e32 v17, v103, v17
	v_cvt_pk_bf16_f32 v4, v102, v103
	v_cvt_pk_bf16_f32 v5, v104, v105
	v_cvt_pk_bf16_f32 v6, v106, v107
	v_cvt_pk_bf16_f32 v7, v108, v109
	s_waitcnt lgkmcnt(10)
	v_mfma_f32_32x32x16_bf16 v[50:65], v[82:85], v[86:89], v[50:65]
	ds_read_b64_tr_b16 v[98:99], v246 offset:34816
	ds_read_b64_tr_b16 v[100:101], v246 offset:35328
	ds_read_b128 v[228:231], v240 offset:6144
	v_add_f32_e32 v17, v104, v17
	v_add_f32_e32 v17, v105, v17
	v_add_f32_e32 v17, v106, v17
	v_add_f32_e32 v17, v107, v17
	s_waitcnt lgkmcnt(10)
	v_mfma_f32_32x32x16_bf16 v[66:81], v[82:85], v[90:93], v[66:81]
	ds_read_b64_tr_b16 v[86:87], v246 offset:38912
	ds_read_b64_tr_b16 v[88:89], v246 offset:39424
	ds_read_b128 v[232:235], v240 offset:6656
	v_add_f32_e32 v17, v108, v17
	v_add_f32_e32 v17, v109, v17
	v_add_f32_e32 v17, 0, v17
	s_waitcnt lgkmcnt(10)
	v_mfma_f32_32x32x16_bf16 v[18:33], v[12:15], v[8:11], v[18:33]
	ds_read_b64_tr_b16 v[82:83], v246 offset:27648
	ds_read_b64_tr_b16 v[84:85], v246 offset:28160
	s_cmpk_lt_u32 s84, 0x100
	s_cbranch_scc0 .Lattn_kdma_5
	s_add_i32 s4, s89, s80
	s_add_u32 s58, s50, 0xc0000
	s_addc_u32 s59, s51, 0
	s_mov_b32 s5, m0
	s_mov_b32 m0, s4
	s_nop 0
	global_load_lds_dwordx4 v252, s[58:59]
	s_mov_b32 m0, s5
; __device__ __forceinline__ int crow(int r,int hi){return (r&3)+8*(r>>2)+4*hi;}
; __device__ __forceinline__ float max3f(float a,float b,float c){float r;asm("v_max3_f32 %0, %1, %2, %3":"=v"(r):"v"(a),"v"(b),"v"(c));return r;}
; __device__ __forceinline__ float max2f(float a,float b){float r;asm("v_max_f32_e32 %0, %1, %2":"=v"(r):"v"(a),"v"(b));return r;}
;   #define PVG(i,PW,VF,NEXTI,X0,X1,Y0,Y1,EXTRA) do{ S.o[(i)&3]=MF32(__builtin_bit_cast(bf16x8,PW),VF,S.o[(i)&3]); if((NEXTI)<16){ VF=vfrag(vp,(NEXTI)<16?(NEXTI):0); } sa+=X0; sa+=X1; sa+=Y0; sa+=Y1; EXTRA; SB(); }while(0)
; template<int THRL,bool FIRST> __device__ __forceinline__ void decide(float rm,St&S,float*wsf,int r32,int hi){
;     ...
;   else if(__any(rm-S.mhat>(float)THRL)){
;     const float dl=__builtin_fmaxf(rm-S.mhat,0.f); S.mhat+=dl;
;     const float f=__builtin_amdgcn_exp2f(-dl); S.l_reg*=f; if(hi==0)wsf[r32]=f;
;     asm volatile("s_waitcnt lgkmcnt(0)":::"memory");
;     #pragma unroll
;     for(int r=0;r<16;++r){ const float fr=wsf[crow(r,hi)];
;       #pragma unroll
;       for(int d=0;d<4;++d)S.o[d][r]*=fr; }
; template<int THRL,bool FIRST> __device__ __forceinline__ void step_main(f32x16&p0,f32x16&p1,f32x16&n0,f32x16&n1,St&S,lds_cptr kpn,lds_cptr qp,lds_cptr vp,float*wsf,int r32,int hi,float&rm){
;     ...
;   float ma,mb;
;     ...
;   PVG(8,pw2,vfa,12,0.f,0.f,0.f,0.f, do{ma=max3f(n0[0],n0[1],n1[0]);mb=max3f(n0[2],n0[3],n1[1]);PINAB();}while(0));
;   PVG(9,pw2,vfb,13,0.f,0.f,0.f,0.f, do{ma=max3f(ma,n1[2],n1[3]);mb=max3f(mb,n0[4],n0[5]);PINAB();}while(0));
;   PVG(10,pw2,vfc,14,0.f,0.f,0.f,0.f, do{ma=max3f(ma,n0[6],n0[7]);mb=max3f(mb,n1[4],n1[5]);PINAB();}while(0));
;   PVG(11,pw2,vfd,15,0.f,0.f,0.f,0.f, do{ma=max3f(ma,n1[6],n1[7]);mb=max3f(mb,n0[8],n0[9]);PINAB();}while(0));
;   PVG(12,pw3,vfa,16,0.f,0.f,0.f,0.f, do{ma=max3f(ma,n0[10],n0[11]);mb=max3f(mb,n1[8],n1[9]);PINAB();}while(0));
;   PVG(13,pw3,vfb,16,0.f,0.f,0.f,0.f, do{ma=max3f(ma,n1[10],n1[11]);mb=max3f(mb,n0[12],n0[13]);PINAB();}while(0));
;   PVG(14,pw3,vfc,16,0.f,0.f,0.f,0.f, do{ma=max3f(ma,n0[14],n0[15]);mb=max3f(mb,n1[12],n1[13]);PINAB();}while(0));
;   PVG(15,pw3,vfd,16,0.f,0.f,0.f,0.f, do{ma=max3f(ma,n1[14],n1[15]);ma=max2f(ma,mb);PINAB();}while(0));
;     ...
;   { auto rr=__builtin_amdgcn_permlane32_swap(__float_as_uint(ma),__float_as_uint(ma),false,false); rm=max2f(__uint_as_float(rr[0]),__uint_as_float(rr[1])); }
.Lattn_kdma_5:
	v_max3_f32 v90, v130, v131, v114
	v_max3_f32 v91, v132, v133, v115
	s_nop 0
	s_waitcnt lgkmcnt(9)
	v_mfma_f32_32x32x16_bf16 v[34:49], v[12:15], v[94:97], v[34:49]
	ds_read_b64_tr_b16 v[8:9], v246 offset:31744
	ds_read_b64_tr_b16 v[10:11], v246 offset:32256
	v_max3_f32 v102, v90, v116, v117
	v_max3_f32 v103, v91, v134, v135
	s_nop 0
	s_waitcnt lgkmcnt(8)
	v_mfma_f32_32x32x16_bf16 v[50:65], v[12:15], v[98:101], v[50:65]
	ds_read_b64_tr_b16 v[90:91], v246 offset:35840
	ds_read_b64_tr_b16 v[92:93], v246 offset:36352
	v_max3_f32 v102, v102, v136, v137
	v_max3_f32 v103, v103, v118, v119
	s_nop 0
	s_waitcnt lgkmcnt(7)
	v_mfma_f32_32x32x16_bf16 v[66:81], v[12:15], v[86:89], v[66:81]
	ds_read_b64_tr_b16 v[94:95], v246 offset:39936
	ds_read_b64_tr_b16 v[96:97], v246 offset:40448
	v_max3_f32 v98, v102, v120, v121
	v_max3_f32 v99, v103, v138, v139
	s_nop 0
	s_waitcnt lgkmcnt(6)
	v_mfma_f32_32x32x16_bf16 v[18:33], v[4:7], v[82:85], v[18:33]
	s_cmpk_lt_u32 s84, 0x100
	s_cbranch_scc1 .Lattn_kdma_6
	s_add_i32 s4, s89, s80
	s_add_u32 s58, s50, 0xc0000
	s_addc_u32 s59, s51, 0
	s_mov_b32 s5, m0
	s_mov_b32 m0, s4
	s_nop 0
	global_load_lds_dwordx4 v252, s[58:59]
	s_mov_b32 m0, s5
.Lattn_kdma_6:
	s_add_i32 s4, s86, 0x2000
	s_cmpk_lg_i32 s86, 0x4000
	s_cselect_b32 s89, s4, 0
	v_max3_f32 v12, v98, v140, v141
	v_max3_f32 v13, v99, v122, v123
	s_nop 0
	s_waitcnt lgkmcnt(4)
	v_mfma_f32_32x32x16_bf16 v[34:49], v[4:7], v[8:11], v[34:49]
	v_max3_f32 v12, v12, v124, v125
	v_max3_f32 v13, v13, v142, v143
	s_nop 0
	s_waitcnt lgkmcnt(2)
	v_mfma_f32_32x32x16_bf16 v[50:65], v[4:7], v[90:93], v[50:65]
	v_max3_f32 v8, v12, v144, v145
	v_max3_f32 v9, v13, v126, v127
	s_nop 0
	s_waitcnt lgkmcnt(0)
	v_mfma_f32_32x32x16_bf16 v[66:81], v[4:7], v[94:97], v[66:81]
	v_max3_f32 v8, v8, v128, v129
	s_nop 0
	v_max_f32_e32 v8, v8, v9
	s_nop 0
	v_mov_b32_e32 v162, v8
	v_mov_b32_e32 v163, v8
	s_waitcnt vmcnt(1) lgkmcnt(0)
	s_barrier
	v_permlane32_swap_b32_e32 v162, v163
	v_max_f32_e32 v94, v162, v163
	v_add_f32_e32 v17, v251, v17
	v_cmp_lt_f32_e32 vcc, s67, v94
	s_cbranch_vccz .LBB0_435
	v_max_f32_e32 v94, v94, v94
	v_max_f32_e32 v94, 0, v94
	v_exp_f32_e64 v95, -v94
	s_and_saveexec_b64 s[58:59], s[6:7]
	s_cbranch_execz .LBB0_434
	ds_write_b32 v16, v95
	s_branch .LBB0_434
